# flash loops P.V sections (28 full-tile bodies): V-fragment ds_read2_b64 rotate through 4 register quads, issued in MFMA shadows, counted lgkmcnt per MFMA
# speedup vs baseline: 1.0251x; 1.0123x over previous
; DI unsigned pack2(float a, float b) { f32x2 v = {a, b}; bf16x2_t r = __builtin_convertvector(v, bf16x2_t); return __builtin_bit_cast(unsigned, r); }
; DI f32x16 mfma32(bf16x8 a, bf16x8 b, f32x16 c) { return __builtin_amdgcn_mfma_f32_32x32x16_bf16(a, b, c, 0, 0, 0); }
;     ...
;   const float mn = fmaxf(m, mx); const float alpha = __builtin_amdgcn_exp2f(m - mn);
;   const float neg = (MODE == 2 && !lanesel) ? NINF : -mn;
;   float ps = 0.f;
; #pragma unroll
;   for (int k2 = 0; k2 < 2; ++k2)
; #pragma unroll
;     for (int i = 0; i < 16; ++i) {
;       if (!(HM & (1 << k2))) continue;
;       const float pv = (MODE == 1) ? __builtin_amdgcn_exp2f(s[k2][i] + neg) : __builtin_amdgcn_exp2f(fmaf(s[k2][i], L2E, neg));
;       s[k2][i] = pv; ps += pv;
;     }
;   l = l * alpha + ps;
;   if (__builtin_amdgcn_ballot_w64(mn != m) != 0ull) {
; #pragma unroll
;     for (int dt = 0; dt < 2; ++dt)
; #pragma unroll
;       for (int i = 0; i < 16; ++i) o[dt][i] *= alpha;
;   }
;   m = mn;
; #pragma unroll
;   for (int st = 0; st < 4; ++st) {
;     if (!(HM & (1 << (st >> 1)))) continue;
;     const int k2 = st >> 1, b8 = 8 * (st & 1);
;     const u32x4 pw = {pack2(s[k2][b8], s[k2][b8 + 1]), pack2(s[k2][b8 + 2], s[k2][b8 + 3]), pack2(s[k2][b8 + 4], s[k2][b8 + 5]), pack2(s[k2][b8 + 6], s[k2][b8 + 7])};
;     const bf16x8 pb = __builtin_bit_cast(bf16x8, pw);
; #pragma unroll
;     for (int dt = 0; dt < 2; ++dt) {
;       const s16x4 lo = *(const s16x4*)(Vs + (32 * dt + r) * LSTR + 16 * st + 4 * h);
;       const s16x4 hi = *(const s16x4*)(Vs + (32 * dt + r) * LSTR + 16 * st + 8 + 4 * h);
;       const bf16x8 a = __builtin_shufflevector(lo, hi, 0, 1, 2, 3, 4, 5, 6, 7);
;       o[dt] = mfma32(a, pb, o[dt]);
;     }
;   }
.LBB0_477:
	v_fma_f32 v86, v86, s34, -v158
	v_exp_f32_e32 v86, v86
	v_fma_f32 v87, v87, s34, -v158
	v_exp_f32_e32 v87, v87
	v_fma_f32 v88, v88, s34, -v158
	v_exp_f32_e32 v88, v88
	v_fma_f32 v89, v89, s34, -v158
	v_exp_f32_e32 v89, v89
	v_fma_f32 v90, v90, s34, -v158
	v_add_f32_e32 v194, 0, v86
	v_exp_f32_e32 v90, v90
	v_fma_f32 v192, v192, s34, -v158
	v_add_f32_e32 v194, v87, v194
	v_exp_f32_e32 v192, v192
	v_fma_f32 v191, v191, s34, -v158
	v_add_f32_e32 v194, v88, v194
	v_exp_f32_e32 v191, v191
	v_fma_f32 v193, v193, s34, -v158
	v_add_f32_e32 v194, v89, v194
	v_exp_f32_e32 v193, v193
	v_fma_f32 v188, v188, s34, -v158
	v_add_f32_e32 v194, v90, v194
	v_exp_f32_e32 v188, v188
	v_fma_f32 v190, v190, s34, -v158
	v_add_f32_e32 v194, v192, v194
	v_exp_f32_e32 v190, v190
	v_fma_f32 v189, v189, s34, -v158
	v_add_f32_e32 v194, v191, v194
	v_exp_f32_e32 v189, v189
	v_fma_f32 v187, v187, s34, -v158
	v_add_f32_e32 v194, v193, v194
	v_exp_f32_e32 v187, v187
	v_fma_f32 v186, v186, s34, -v158
	v_add_f32_e32 v194, v188, v194
	v_exp_f32_e32 v186, v186
	v_fma_f32 v185, v185, s34, -v158
	v_add_f32_e32 v194, v190, v194
	v_exp_f32_e32 v185, v185
	v_fma_f32 v184, v184, s34, -v158
	v_add_f32_e32 v194, v189, v194
	v_exp_f32_e32 v184, v184
	v_fma_f32 v182, v182, s34, -v158
	v_add_f32_e32 v194, v187, v194
	v_exp_f32_e32 v182, v182
	v_fma_f32 v164, v164, s34, -v158
	v_add_f32_e32 v194, v186, v194
	v_exp_f32_e32 v164, v164
	v_fma_f32 v162, v162, s34, -v158
	v_add_f32_e32 v194, v185, v194
	v_exp_f32_e32 v162, v162
	v_fma_f32 v160, v160, s34, -v158
	v_add_f32_e32 v194, v184, v194
	v_exp_f32_e32 v195, v160
	v_add_f32_e32 v194, v182, v194
	v_add_f32_e32 v194, v164, v194
	v_add_f32_e32 v194, v162, v194
	v_fma_f32 v97, v97, s34, -v158
	v_add_f32_e32 v160, v195, v194
	v_exp_f32_e32 v194, v97
	v_fma_f32 v92, v92, s34, -v158
	v_exp_f32_e32 v209, v92
	v_fma_f32 v91, v91, s34, -v158
	v_exp_f32_e32 v210, v91
	v_add_f32_e32 v97, v194, v160
	v_add_f32_e32 v92, v209, v97
	v_cvt_pk_bf16_f32 v86, v86, v87
	v_add_f32_e32 v91, v210, v92
	v_fma_f32 v92, v93, s34, -v158
	v_exp_f32_e32 v211, v92
	v_fma_f32 v92, v94, s34, -v158
	v_exp_f32_e32 v212, v92
	v_fma_f32 v92, v95, s34, -v158
	v_exp_f32_e32 v213, v92
	v_fma_f32 v92, v96, s34, -v158
	v_exp_f32_e32 v214, v92
	v_fma_f32 v92, v161, s34, -v158
	v_add_f32_e32 v91, v211, v91
	v_exp_f32_e32 v161, v92
	v_fma_f32 v92, v163, s34, -v158
	v_add_f32_e32 v91, v212, v91
	v_exp_f32_e32 v163, v92
	v_fma_f32 v92, v165, s34, -v158
	v_add_f32_e32 v91, v213, v91
	v_exp_f32_e32 v165, v92
	v_fma_f32 v92, v180, s34, -v158
	v_add_f32_e32 v91, v214, v91
	v_exp_f32_e32 v180, v92
	v_fma_f32 v92, v181, s34, -v158
	v_add_f32_e32 v91, v161, v91
	v_exp_f32_e32 v181, v92
	v_fma_f32 v92, v183, s34, -v158
	v_add_f32_e32 v91, v163, v91
	v_exp_f32_e32 v183, v92
	v_add_f32_e32 v91, v165, v91
	v_add_f32_e32 v91, v180, v91
	v_add_f32_e32 v91, v181, v91
	v_add_f32_e32 v160, v183, v91
	v_fmac_f32_e32 v160, v159, v0
	v_add_u32_e32 v0, 0x2000, v198
	v_cvt_pk_bf16_f32 v87, v88, v89
	v_cvt_pk_bf16_f32 v88, v90, v192
	v_add_u32_e32 v242, 0x3000, v198
	ds_read2_b64 v[90:93], v0 offset0:128 offset1:130
	ds_read2_b64 v[94:97], v0 offset0:132 offset1:134
	ds_read2_b64 v[234:237], v242 offset0:192 offset1:194
	ds_read2_b64 v[238:241], v242 offset0:196 offset1:198
	v_cvt_pk_bf16_f32 v89, v191, v193
	v_add_u32_e32 v191, 0x3000, v198
	s_mov_b64 s[6:7], 0
	s_waitcnt lgkmcnt(3)
	v_mfma_f32_32x32x16_bf16 v[34:49], v[90:93], v[86:89], v[2:17]
	ds_read2_b64 v[90:93], v0 offset0:136 offset1:138
	s_waitcnt lgkmcnt(2)
	v_mfma_f32_32x32x16_bf16 v[50:65], v[234:237], v[86:89], v[18:33]
	ds_read2_b64 v[234:237], v242 offset0:200 offset1:202
	v_cvt_pk_bf16_f32 v86, v188, v190
	v_cvt_pk_bf16_f32 v87, v189, v187
	v_cvt_pk_bf16_f32 v88, v186, v185
	v_cvt_pk_bf16_f32 v89, v184, v182
	s_waitcnt lgkmcnt(2)
	s_nop 0
	v_mfma_f32_32x32x16_bf16 v[50:65], v[238:241], v[86:89], v[50:65]
	ds_read2_b64 v[238:241], v0 offset0:140 offset1:142
	v_mfma_f32_32x32x16_bf16 v[34:49], v[94:97], v[86:89], v[34:49]
	ds_read2_b64 v[94:97], v242 offset0:204 offset1:206
	v_cvt_pk_bf16_f32 v86, v164, v162
	v_cvt_pk_bf16_f32 v87, v195, v194
	v_cvt_pk_bf16_f32 v88, v209, v210
	v_cvt_pk_bf16_f32 v89, v211, v212
	s_waitcnt lgkmcnt(3)
	s_nop 0
	v_mfma_f32_32x32x16_bf16 v[34:49], v[90:93], v[86:89], v[34:49]
	s_waitcnt lgkmcnt(2)
	v_mfma_f32_32x32x16_bf16 v[50:65], v[234:237], v[86:89], v[50:65]
	v_cvt_pk_bf16_f32 v86, v213, v214
	v_cvt_pk_bf16_f32 v87, v161, v163
	v_cvt_pk_bf16_f32 v88, v165, v180
	v_cvt_pk_bf16_f32 v89, v181, v183
	s_waitcnt lgkmcnt(1)
	s_nop 0
	v_mfma_f32_32x32x16_bf16 v[2:17], v[238:241], v[86:89], v[34:49]
	s_waitcnt lgkmcnt(0)
	v_mfma_f32_32x32x16_bf16 v[18:33], v[94:97], v[86:89], v[50:65]

; DI unsigned pack2(float a, float b) { f32x2 v = {a, b}; bf16x2_t r = __builtin_convertvector(v, bf16x2_t); return __builtin_bit_cast(unsigned, r); }
; DI f32x16 mfma32(bf16x8 a, bf16x8 b, f32x16 c) { return __builtin_amdgcn_mfma_f32_32x32x16_bf16(a, b, c, 0, 0, 0); }
;     ...
;   const float mn = fmaxf(m, mx); const float alpha = __builtin_amdgcn_exp2f(m - mn);
;   const float neg = (MODE == 2 && !lanesel) ? NINF : -mn;
;   float ps = 0.f;
; #pragma unroll
;   for (int k2 = 0; k2 < 2; ++k2)
; #pragma unroll
;     for (int i = 0; i < 16; ++i) {
;       if (!(HM & (1 << k2))) continue;
;       const float pv = (MODE == 1) ? __builtin_amdgcn_exp2f(s[k2][i] + neg) : __builtin_amdgcn_exp2f(fmaf(s[k2][i], L2E, neg));
;       s[k2][i] = pv; ps += pv;
;     }
;   l = l * alpha + ps;
;   if (__builtin_amdgcn_ballot_w64(mn != m) != 0ull) {
; #pragma unroll
;     for (int dt = 0; dt < 2; ++dt)
; #pragma unroll
;       for (int i = 0; i < 16; ++i) o[dt][i] *= alpha;
;   }
;   m = mn;
; #pragma unroll
;   for (int st = 0; st < 4; ++st) {
;     if (!(HM & (1 << (st >> 1)))) continue;
;     const int k2 = st >> 1, b8 = 8 * (st & 1);
;     const u32x4 pw = {pack2(s[k2][b8], s[k2][b8 + 1]), pack2(s[k2][b8 + 2], s[k2][b8 + 3]), pack2(s[k2][b8 + 4], s[k2][b8 + 5]), pack2(s[k2][b8 + 6], s[k2][b8 + 7])};
;     const bf16x8 pb = __builtin_bit_cast(bf16x8, pw);
; #pragma unroll
;     for (int dt = 0; dt < 2; ++dt) {
;       const s16x4 lo = *(const s16x4*)(Vs + (32 * dt + r) * LSTR + 16 * st + 4 * h);
;       const s16x4 hi = *(const s16x4*)(Vs + (32 * dt + r) * LSTR + 16 * st + 8 + 4 * h);
;       const bf16x8 a = __builtin_shufflevector(lo, hi, 0, 1, 2, 3, 4, 5, 6, 7);
;       o[dt] = mfma32(a, pb, o[dt]);
;     }
;   }
.LBB0_481:
	v_fma_f32 v82, v82, s34, -v158
	v_exp_f32_e32 v82, v82
	v_fma_f32 v83, v83, s34, -v158
	v_exp_f32_e32 v83, v83
	v_fma_f32 v84, v84, s34, -v158
	v_exp_f32_e32 v84, v84
	v_fma_f32 v85, v85, s34, -v158
	v_exp_f32_e32 v85, v85
	v_fma_f32 v86, v86, s34, -v158
	v_add_f32_e32 v160, 0, v82
	v_exp_f32_e32 v86, v86
	v_fma_f32 v87, v87, s34, -v158
	v_add_f32_e32 v160, v83, v160
	v_exp_f32_e32 v87, v87
	v_fma_f32 v88, v88, s34, -v158
	v_add_f32_e32 v160, v84, v160
	v_exp_f32_e32 v88, v88
	v_fma_f32 v89, v89, s34, -v158
	v_add_f32_e32 v160, v85, v160
	v_exp_f32_e32 v89, v89
	v_fma_f32 v90, v90, s34, -v158
	v_add_f32_e32 v160, v86, v160
	v_exp_f32_e32 v90, v90
	v_fma_f32 v91, v91, s34, -v158
	v_add_f32_e32 v160, v87, v160
	v_exp_f32_e32 v91, v91
	v_fma_f32 v92, v92, s34, -v158
	v_add_f32_e32 v160, v88, v160
	v_exp_f32_e32 v92, v92
	v_fma_f32 v93, v93, s34, -v158
	v_add_f32_e32 v160, v89, v160
	v_exp_f32_e32 v93, v93
	v_fma_f32 v94, v94, s34, -v158
	v_add_f32_e32 v160, v90, v160
	v_exp_f32_e32 v94, v94
	v_fma_f32 v95, v95, s34, -v158
	v_add_f32_e32 v160, v91, v160
	v_exp_f32_e32 v95, v95
	v_fma_f32 v96, v96, s34, -v158
	v_add_f32_e32 v160, v92, v160
	v_exp_f32_e32 v96, v96
	v_fma_f32 v97, v97, s34, -v158
	v_add_f32_e32 v160, v93, v160
	v_exp_f32_e32 v97, v97
	v_fma_f32 v66, v66, s34, -v158
	v_add_f32_e32 v160, v94, v160
	v_exp_f32_e32 v161, v66
	v_fma_f32 v67, v67, s34, -v158
	v_add_f32_e32 v160, v95, v160
	v_exp_f32_e32 v162, v67
	v_fma_f32 v67, v68, s34, -v158
	v_add_f32_e32 v160, v96, v160
	v_exp_f32_e32 v163, v67
	v_fma_f32 v67, v69, s34, -v158
	v_add_f32_e32 v160, v97, v160
	v_exp_f32_e32 v164, v67
	v_fma_f32 v67, v70, s34, -v158
	v_add_f32_e32 v66, v161, v160
	v_exp_f32_e32 v165, v67
	v_fma_f32 v67, v71, s34, -v158
	v_add_f32_e32 v66, v162, v66
	v_exp_f32_e32 v180, v67
	v_fma_f32 v67, v72, s34, -v158
	v_add_f32_e32 v66, v163, v66
	v_exp_f32_e32 v181, v67
	v_fma_f32 v67, v73, s34, -v158
	v_add_f32_e32 v66, v164, v66
	v_exp_f32_e32 v182, v67
	v_fma_f32 v67, v74, s34, -v158
	v_add_f32_e32 v66, v165, v66
	v_exp_f32_e32 v183, v67
	v_fma_f32 v67, v75, s34, -v158
	v_add_f32_e32 v66, v180, v66
	v_exp_f32_e32 v184, v67
	v_fma_f32 v67, v76, s34, -v158
	v_add_f32_e32 v66, v181, v66
	v_exp_f32_e32 v185, v67
	v_fma_f32 v67, v77, s34, -v158
	v_add_f32_e32 v66, v182, v66
	v_exp_f32_e32 v186, v67
	v_fma_f32 v67, v78, s34, -v158
	v_add_f32_e32 v66, v183, v66
	v_exp_f32_e32 v78, v67
	v_fma_f32 v67, v79, s34, -v158
	v_add_f32_e32 v66, v184, v66
	v_exp_f32_e32 v79, v67
	v_fma_f32 v67, v80, s34, -v158
	v_add_f32_e32 v66, v185, v66
	v_exp_f32_e32 v80, v67
	v_fma_f32 v67, v81, s34, -v158
	v_add_f32_e32 v66, v186, v66
	v_exp_f32_e32 v81, v67
	v_add_f32_e32 v66, v78, v66
	v_add_f32_e32 v66, v79, v66
	v_add_f32_e32 v66, v80, v66
	v_add_f32_e32 v160, v81, v66
	v_fmac_f32_e32 v160, v159, v0
	v_add_u32_e32 v0, 0x2000, v198
	v_add_u32_e32 v242, 0x3000, v198
	ds_read2_b64 v[70:73], v0 offset0:128 offset1:130
	ds_read2_b64 v[74:77], v0 offset0:132 offset1:134
	ds_read2_b64 v[234:237], v242 offset0:192 offset1:194
	ds_read2_b64 v[238:241], v242 offset0:196 offset1:198
	v_cvt_pk_bf16_f32 v66, v82, v83
	v_cvt_pk_bf16_f32 v67, v84, v85
	v_cvt_pk_bf16_f32 v68, v86, v87
	v_cvt_pk_bf16_f32 v69, v88, v89
	v_add_u32_e32 v82, 0x3000, v198
	s_waitcnt lgkmcnt(3)
	v_mfma_f32_32x32x16_bf16 v[34:49], v[70:73], v[66:69], v[2:17]
	ds_read2_b64 v[70:73], v0 offset0:136 offset1:138
	s_waitcnt lgkmcnt(2)
	v_mfma_f32_32x32x16_bf16 v[50:65], v[234:237], v[66:69], v[18:33]
	ds_read2_b64 v[234:237], v242 offset0:200 offset1:202
	v_cvt_pk_bf16_f32 v66, v90, v91
	v_cvt_pk_bf16_f32 v67, v92, v93
	v_cvt_pk_bf16_f32 v68, v94, v95
	v_cvt_pk_bf16_f32 v69, v96, v97
	s_waitcnt lgkmcnt(2)
	s_nop 0
	v_mfma_f32_32x32x16_bf16 v[50:65], v[238:241], v[66:69], v[50:65]
	ds_read2_b64 v[238:241], v0 offset0:140 offset1:142
	v_mfma_f32_32x32x16_bf16 v[34:49], v[74:77], v[66:69], v[34:49]
	ds_read2_b64 v[74:77], v242 offset0:204 offset1:206
	v_cvt_pk_bf16_f32 v66, v161, v162
	v_cvt_pk_bf16_f32 v67, v163, v164
	v_cvt_pk_bf16_f32 v68, v165, v180
	v_cvt_pk_bf16_f32 v69, v181, v182
	s_waitcnt lgkmcnt(3)
	s_nop 0
	v_mfma_f32_32x32x16_bf16 v[34:49], v[70:73], v[66:69], v[34:49]
	s_waitcnt lgkmcnt(2)
	v_mfma_f32_32x32x16_bf16 v[50:65], v[234:237], v[66:69], v[50:65]
	v_cvt_pk_bf16_f32 v66, v183, v184
	v_cvt_pk_bf16_f32 v67, v185, v186
	v_cvt_pk_bf16_f32 v68, v78, v79
	v_cvt_pk_bf16_f32 v69, v80, v81
	s_waitcnt lgkmcnt(1)
	s_nop 0
	v_mfma_f32_32x32x16_bf16 v[2:17], v[238:241], v[66:69], v[34:49]
	s_waitcnt lgkmcnt(0)
	v_mfma_f32_32x32x16_bf16 v[18:33], v[74:77], v[66:69], v[50:65]

; DI unsigned pack2(float a, float b) { f32x2 v = {a, b}; bf16x2_t r = __builtin_convertvector(v, bf16x2_t); return __builtin_bit_cast(unsigned, r); }
; DI f32x16 mfma32(bf16x8 a, bf16x8 b, f32x16 c) { return __builtin_amdgcn_mfma_f32_32x32x16_bf16(a, b, c, 0, 0, 0); }
;     ...
;   const float mn = fmaxf(m, mx); const float alpha = __builtin_amdgcn_exp2f(m - mn);
;   const float neg = (MODE == 2 && !lanesel) ? NINF : -mn;
;   float ps = 0.f;
; #pragma unroll
;   for (int k2 = 0; k2 < 2; ++k2)
; #pragma unroll
;     for (int i = 0; i < 16; ++i) {
;       if (!(HM & (1 << k2))) continue;
;       const float pv = (MODE == 1) ? __builtin_amdgcn_exp2f(s[k2][i] + neg) : __builtin_amdgcn_exp2f(fmaf(s[k2][i], L2E, neg));
;       s[k2][i] = pv; ps += pv;
;     }
;   l = l * alpha + ps;
;   if (__builtin_amdgcn_ballot_w64(mn != m) != 0ull) {
; #pragma unroll
;     for (int dt = 0; dt < 2; ++dt)
; #pragma unroll
;       for (int i = 0; i < 16; ++i) o[dt][i] *= alpha;
;   }
;   m = mn;
; #pragma unroll
;   for (int st = 0; st < 4; ++st) {
;     if (!(HM & (1 << (st >> 1)))) continue;
;     const int k2 = st >> 1, b8 = 8 * (st & 1);
;     const u32x4 pw = {pack2(s[k2][b8], s[k2][b8 + 1]), pack2(s[k2][b8 + 2], s[k2][b8 + 3]), pack2(s[k2][b8 + 4], s[k2][b8 + 5]), pack2(s[k2][b8 + 6], s[k2][b8 + 7])};
;     const bf16x8 pb = __builtin_bit_cast(bf16x8, pw);
; #pragma unroll
;     for (int dt = 0; dt < 2; ++dt) {
;       const s16x4 lo = *(const s16x4*)(Vs + (32 * dt + r) * LSTR + 16 * st + 4 * h);
;       const s16x4 hi = *(const s16x4*)(Vs + (32 * dt + r) * LSTR + 16 * st + 8 + 4 * h);
;       const bf16x8 a = __builtin_shufflevector(lo, hi, 0, 1, 2, 3, 4, 5, 6, 7);
;       o[dt] = mfma32(a, pb, o[dt]);
;     }
;   }
.LBB0_505:
	v_fma_f32 v86, v86, s34, -v157
	v_exp_f32_e32 v86, v86
	v_fma_f32 v87, v87, s34, -v157
	v_exp_f32_e32 v87, v87
	v_fma_f32 v88, v88, s34, -v157
	v_exp_f32_e32 v88, v88
	v_fma_f32 v89, v89, s34, -v157
	v_exp_f32_e32 v89, v89
	v_fma_f32 v90, v90, s34, -v157
	v_add_f32_e32 v194, 0, v86
	v_exp_f32_e32 v90, v90
	v_fma_f32 v192, v192, s34, -v157
	v_add_f32_e32 v194, v87, v194
	v_exp_f32_e32 v192, v192
	v_fma_f32 v191, v191, s34, -v157
	v_add_f32_e32 v194, v88, v194
	v_exp_f32_e32 v191, v191
	v_fma_f32 v193, v193, s34, -v157
	v_add_f32_e32 v194, v89, v194
	v_exp_f32_e32 v193, v193
	v_fma_f32 v188, v188, s34, -v157
	v_add_f32_e32 v194, v90, v194
	v_exp_f32_e32 v188, v188
	v_fma_f32 v190, v190, s34, -v157
	v_add_f32_e32 v194, v192, v194
	v_exp_f32_e32 v190, v190
	v_fma_f32 v189, v189, s34, -v157
	v_add_f32_e32 v194, v191, v194
	v_exp_f32_e32 v189, v189
	v_fma_f32 v187, v187, s34, -v157
	v_add_f32_e32 v194, v193, v194
	v_exp_f32_e32 v187, v187
	v_fma_f32 v186, v186, s34, -v157
	v_add_f32_e32 v194, v188, v194
	v_exp_f32_e32 v186, v186
	v_fma_f32 v185, v185, s34, -v157
	v_add_f32_e32 v194, v190, v194
	v_exp_f32_e32 v185, v185
	v_fma_f32 v184, v184, s34, -v157
	v_add_f32_e32 v194, v189, v194
	v_exp_f32_e32 v184, v184
	v_fma_f32 v182, v182, s34, -v157
	v_add_f32_e32 v194, v187, v194
	v_exp_f32_e32 v182, v182
	v_fma_f32 v164, v164, s34, -v157
	v_add_f32_e32 v194, v186, v194
	v_exp_f32_e32 v164, v164
	v_fma_f32 v162, v162, s34, -v157
	v_add_f32_e32 v194, v185, v194
	v_exp_f32_e32 v162, v162
	v_fma_f32 v159, v159, s34, -v157
	v_add_f32_e32 v194, v184, v194
	v_exp_f32_e32 v195, v159
	v_add_f32_e32 v194, v182, v194
	v_add_f32_e32 v194, v164, v194
	v_add_f32_e32 v194, v162, v194
	v_fma_f32 v97, v97, s34, -v157
	v_add_f32_e32 v159, v195, v194
	v_exp_f32_e32 v194, v97
	v_fma_f32 v92, v92, s34, -v157
	v_exp_f32_e32 v209, v92
	v_fma_f32 v91, v91, s34, -v157
	v_exp_f32_e32 v210, v91
	v_add_f32_e32 v97, v194, v159
	v_add_f32_e32 v92, v209, v97
	v_cvt_pk_bf16_f32 v86, v86, v87
	v_add_f32_e32 v91, v210, v92
	v_fma_f32 v92, v93, s34, -v157
	v_exp_f32_e32 v211, v92
	v_fma_f32 v92, v94, s34, -v157
	v_exp_f32_e32 v212, v92
	v_fma_f32 v92, v95, s34, -v157
	v_exp_f32_e32 v213, v92
	v_fma_f32 v92, v96, s34, -v157
	v_exp_f32_e32 v214, v92
	v_fma_f32 v92, v161, s34, -v157
	v_add_f32_e32 v91, v211, v91
	v_exp_f32_e32 v161, v92
	v_fma_f32 v92, v163, s34, -v157
	v_add_f32_e32 v91, v212, v91
	v_exp_f32_e32 v163, v92
	v_fma_f32 v92, v165, s34, -v157
	v_add_f32_e32 v91, v213, v91
	v_exp_f32_e32 v165, v92
	v_fma_f32 v92, v180, s34, -v157
	v_add_f32_e32 v91, v214, v91
	v_exp_f32_e32 v180, v92
	v_fma_f32 v92, v181, s34, -v157
	v_add_f32_e32 v91, v161, v91
	v_exp_f32_e32 v181, v92
	v_fma_f32 v92, v183, s34, -v157
	v_add_f32_e32 v91, v163, v91
	v_exp_f32_e32 v183, v92
	v_add_f32_e32 v91, v165, v91
	v_add_f32_e32 v91, v180, v91
	v_add_f32_e32 v91, v181, v91
	v_add_f32_e32 v159, v183, v91
	v_fmac_f32_e32 v159, v160, v0
	v_add_u32_e32 v0, 0x6800, v198
	v_cvt_pk_bf16_f32 v87, v88, v89
	v_cvt_pk_bf16_f32 v88, v90, v192
	v_add_u32_e32 v242, 0x7800, v198
	ds_read2_b64 v[90:93], v0 offset0:128 offset1:130
	ds_read2_b64 v[94:97], v0 offset0:132 offset1:134
	ds_read2_b64 v[234:237], v242 offset0:192 offset1:194
	ds_read2_b64 v[238:241], v242 offset0:196 offset1:198
	v_cvt_pk_bf16_f32 v89, v191, v193
	v_add_u32_e32 v191, 0x7800, v198
	s_mov_b64 s[6:7], 0
	s_waitcnt lgkmcnt(3)
	v_mfma_f32_32x32x16_bf16 v[34:49], v[90:93], v[86:89], v[2:17]
	ds_read2_b64 v[90:93], v0 offset0:136 offset1:138
	s_waitcnt lgkmcnt(2)
	v_mfma_f32_32x32x16_bf16 v[50:65], v[234:237], v[86:89], v[18:33]
	ds_read2_b64 v[234:237], v242 offset0:200 offset1:202
	v_cvt_pk_bf16_f32 v86, v188, v190
	v_cvt_pk_bf16_f32 v87, v189, v187
	v_cvt_pk_bf16_f32 v88, v186, v185
	v_cvt_pk_bf16_f32 v89, v184, v182
	s_waitcnt lgkmcnt(2)
	s_nop 0
	v_mfma_f32_32x32x16_bf16 v[50:65], v[238:241], v[86:89], v[50:65]
	ds_read2_b64 v[238:241], v0 offset0:140 offset1:142
	v_mfma_f32_32x32x16_bf16 v[34:49], v[94:97], v[86:89], v[34:49]
	ds_read2_b64 v[94:97], v242 offset0:204 offset1:206
	v_cvt_pk_bf16_f32 v86, v164, v162
	v_cvt_pk_bf16_f32 v87, v195, v194
	v_cvt_pk_bf16_f32 v88, v209, v210
	v_cvt_pk_bf16_f32 v89, v211, v212
	s_waitcnt lgkmcnt(3)
	s_nop 0
	v_mfma_f32_32x32x16_bf16 v[34:49], v[90:93], v[86:89], v[34:49]
	s_waitcnt lgkmcnt(2)
	v_mfma_f32_32x32x16_bf16 v[50:65], v[234:237], v[86:89], v[50:65]
	v_cvt_pk_bf16_f32 v86, v213, v214
	v_cvt_pk_bf16_f32 v87, v161, v163
	v_cvt_pk_bf16_f32 v88, v165, v180
	v_cvt_pk_bf16_f32 v89, v181, v183
	s_waitcnt lgkmcnt(1)
	s_nop 0
	v_mfma_f32_32x32x16_bf16 v[2:17], v[238:241], v[86:89], v[34:49]
	s_waitcnt lgkmcnt(0)
	v_mfma_f32_32x32x16_bf16 v[18:33], v[94:97], v[86:89], v[50:65]

; DI unsigned pack2(float a, float b) { f32x2 v = {a, b}; bf16x2_t r = __builtin_convertvector(v, bf16x2_t); return __builtin_bit_cast(unsigned, r); }
; DI f32x16 mfma32(bf16x8 a, bf16x8 b, f32x16 c) { return __builtin_amdgcn_mfma_f32_32x32x16_bf16(a, b, c, 0, 0, 0); }
;     ...
;   const float mn = fmaxf(m, mx); const float alpha = __builtin_amdgcn_exp2f(m - mn);
;   const float neg = (MODE == 2 && !lanesel) ? NINF : -mn;
;   float ps = 0.f;
; #pragma unroll
;   for (int k2 = 0; k2 < 2; ++k2)
; #pragma unroll
;     for (int i = 0; i < 16; ++i) {
;       if (!(HM & (1 << k2))) continue;
;       const float pv = (MODE == 1) ? __builtin_amdgcn_exp2f(s[k2][i] + neg) : __builtin_amdgcn_exp2f(fmaf(s[k2][i], L2E, neg));
;       s[k2][i] = pv; ps += pv;
;     }
;   l = l * alpha + ps;
;   if (__builtin_amdgcn_ballot_w64(mn != m) != 0ull) {
; #pragma unroll
;     for (int dt = 0; dt < 2; ++dt)
; #pragma unroll
;       for (int i = 0; i < 16; ++i) o[dt][i] *= alpha;
;   }
;   m = mn;
; #pragma unroll
;   for (int st = 0; st < 4; ++st) {
;     if (!(HM & (1 << (st >> 1)))) continue;
;     const int k2 = st >> 1, b8 = 8 * (st & 1);
;     const u32x4 pw = {pack2(s[k2][b8], s[k2][b8 + 1]), pack2(s[k2][b8 + 2], s[k2][b8 + 3]), pack2(s[k2][b8 + 4], s[k2][b8 + 5]), pack2(s[k2][b8 + 6], s[k2][b8 + 7])};
;     const bf16x8 pb = __builtin_bit_cast(bf16x8, pw);
; #pragma unroll
;     for (int dt = 0; dt < 2; ++dt) {
;       const s16x4 lo = *(const s16x4*)(Vs + (32 * dt + r) * LSTR + 16 * st + 4 * h);
;       const s16x4 hi = *(const s16x4*)(Vs + (32 * dt + r) * LSTR + 16 * st + 8 + 4 * h);
;       const bf16x8 a = __builtin_shufflevector(lo, hi, 0, 1, 2, 3, 4, 5, 6, 7);
;       o[dt] = mfma32(a, pb, o[dt]);
;     }
;   }
.LBB0_509:
	v_fma_f32 v82, v82, s34, -v157
	v_exp_f32_e32 v82, v82
	v_fma_f32 v83, v83, s34, -v157
	v_exp_f32_e32 v83, v83
	v_fma_f32 v84, v84, s34, -v157
	v_exp_f32_e32 v84, v84
	v_fma_f32 v85, v85, s34, -v157
	v_exp_f32_e32 v85, v85
	v_fma_f32 v86, v86, s34, -v157
	v_add_f32_e32 v159, 0, v82
	v_exp_f32_e32 v86, v86
	v_fma_f32 v87, v87, s34, -v157
	v_add_f32_e32 v159, v83, v159
	v_exp_f32_e32 v87, v87
	v_fma_f32 v88, v88, s34, -v157
	v_add_f32_e32 v159, v84, v159
	v_exp_f32_e32 v88, v88
	v_fma_f32 v89, v89, s34, -v157
	v_add_f32_e32 v159, v85, v159
	v_exp_f32_e32 v89, v89
	v_fma_f32 v90, v90, s34, -v157
	v_add_f32_e32 v159, v86, v159
	v_exp_f32_e32 v90, v90
	v_fma_f32 v91, v91, s34, -v157
	v_add_f32_e32 v159, v87, v159
	v_exp_f32_e32 v91, v91
	v_fma_f32 v92, v92, s34, -v157
	v_add_f32_e32 v159, v88, v159
	v_exp_f32_e32 v92, v92
	v_fma_f32 v93, v93, s34, -v157
	v_add_f32_e32 v159, v89, v159
	v_exp_f32_e32 v93, v93
	v_fma_f32 v94, v94, s34, -v157
	v_add_f32_e32 v159, v90, v159
	v_exp_f32_e32 v94, v94
	v_fma_f32 v95, v95, s34, -v157
	v_add_f32_e32 v159, v91, v159
	v_exp_f32_e32 v95, v95
	v_fma_f32 v96, v96, s34, -v157
	v_add_f32_e32 v159, v92, v159
	v_exp_f32_e32 v96, v96
	v_fma_f32 v97, v97, s34, -v157
	v_add_f32_e32 v159, v93, v159
	v_exp_f32_e32 v97, v97
	v_fma_f32 v66, v66, s34, -v157
	v_add_f32_e32 v159, v94, v159
	v_exp_f32_e32 v161, v66
	v_fma_f32 v67, v67, s34, -v157
	v_add_f32_e32 v159, v95, v159
	v_exp_f32_e32 v162, v67
	v_fma_f32 v67, v68, s34, -v157
	v_add_f32_e32 v159, v96, v159
	v_exp_f32_e32 v163, v67
	v_fma_f32 v67, v69, s34, -v157
	v_add_f32_e32 v159, v97, v159
	v_exp_f32_e32 v164, v67
	v_fma_f32 v67, v70, s34, -v157
	v_add_f32_e32 v66, v161, v159
	v_exp_f32_e32 v165, v67
	v_fma_f32 v67, v71, s34, -v157
	v_add_f32_e32 v66, v162, v66
	v_exp_f32_e32 v180, v67
	v_fma_f32 v67, v72, s34, -v157
	v_add_f32_e32 v66, v163, v66
	v_exp_f32_e32 v181, v67
	v_fma_f32 v67, v73, s34, -v157
	v_add_f32_e32 v66, v164, v66
	v_exp_f32_e32 v182, v67
	v_fma_f32 v67, v74, s34, -v157
	v_add_f32_e32 v66, v165, v66
	v_exp_f32_e32 v183, v67
	v_fma_f32 v67, v75, s34, -v157
	v_add_f32_e32 v66, v180, v66
	v_exp_f32_e32 v184, v67
	v_fma_f32 v67, v76, s34, -v157
	v_add_f32_e32 v66, v181, v66
	v_exp_f32_e32 v185, v67
	v_fma_f32 v67, v77, s34, -v157
	v_add_f32_e32 v66, v182, v66
	v_exp_f32_e32 v186, v67
	v_fma_f32 v67, v78, s34, -v157
	v_add_f32_e32 v66, v183, v66
	v_exp_f32_e32 v78, v67
	v_fma_f32 v67, v79, s34, -v157
	v_add_f32_e32 v66, v184, v66
	v_exp_f32_e32 v79, v67
	v_fma_f32 v67, v80, s34, -v157
	v_add_f32_e32 v66, v185, v66
	v_exp_f32_e32 v80, v67
	v_fma_f32 v67, v81, s34, -v157
	v_add_f32_e32 v66, v186, v66
	v_exp_f32_e32 v81, v67
	v_add_f32_e32 v66, v78, v66
	v_add_f32_e32 v66, v79, v66
	v_add_f32_e32 v66, v80, v66
	v_add_f32_e32 v159, v81, v66
	v_fmac_f32_e32 v159, v160, v0
	v_add_u32_e32 v0, 0x6800, v198
	v_add_u32_e32 v242, 0x7800, v198
	ds_read2_b64 v[70:73], v0 offset0:128 offset1:130
	ds_read2_b64 v[74:77], v0 offset0:132 offset1:134
	ds_read2_b64 v[234:237], v242 offset0:192 offset1:194
	ds_read2_b64 v[238:241], v242 offset0:196 offset1:198
	v_cvt_pk_bf16_f32 v66, v82, v83
	v_cvt_pk_bf16_f32 v67, v84, v85
	v_cvt_pk_bf16_f32 v68, v86, v87
	v_cvt_pk_bf16_f32 v69, v88, v89
	v_add_u32_e32 v82, 0x7800, v198
	s_waitcnt lgkmcnt(3)
	v_mfma_f32_32x32x16_bf16 v[34:49], v[70:73], v[66:69], v[2:17]
	ds_read2_b64 v[70:73], v0 offset0:136 offset1:138
	s_waitcnt lgkmcnt(2)
	v_mfma_f32_32x32x16_bf16 v[50:65], v[234:237], v[66:69], v[18:33]
	ds_read2_b64 v[234:237], v242 offset0:200 offset1:202
	v_cvt_pk_bf16_f32 v66, v90, v91
	v_cvt_pk_bf16_f32 v67, v92, v93
	v_cvt_pk_bf16_f32 v68, v94, v95
	v_cvt_pk_bf16_f32 v69, v96, v97
	s_waitcnt lgkmcnt(2)
	s_nop 0
	v_mfma_f32_32x32x16_bf16 v[50:65], v[238:241], v[66:69], v[50:65]
	ds_read2_b64 v[238:241], v0 offset0:140 offset1:142
	v_mfma_f32_32x32x16_bf16 v[34:49], v[74:77], v[66:69], v[34:49]
	ds_read2_b64 v[74:77], v242 offset0:204 offset1:206
	v_cvt_pk_bf16_f32 v66, v161, v162
	v_cvt_pk_bf16_f32 v67, v163, v164
	v_cvt_pk_bf16_f32 v68, v165, v180
	v_cvt_pk_bf16_f32 v69, v181, v182
	s_waitcnt lgkmcnt(3)
	s_nop 0
	v_mfma_f32_32x32x16_bf16 v[34:49], v[70:73], v[66:69], v[34:49]
	s_waitcnt lgkmcnt(2)
	v_mfma_f32_32x32x16_bf16 v[50:65], v[234:237], v[66:69], v[50:65]
	v_cvt_pk_bf16_f32 v66, v183, v184
	v_cvt_pk_bf16_f32 v67, v185, v186
	v_cvt_pk_bf16_f32 v68, v78, v79
	v_cvt_pk_bf16_f32 v69, v80, v81
	s_waitcnt lgkmcnt(1)
	s_nop 0
	v_mfma_f32_32x32x16_bf16 v[2:17], v[238:241], v[66:69], v[34:49]
	s_waitcnt lgkmcnt(0)
	v_mfma_f32_32x32x16_bf16 v[18:33], v[74:77], v[66:69], v[50:65]

; DI unsigned pack2(float a, float b) { f32x2 v = {a, b}; bf16x2_t r = __builtin_convertvector(v, bf16x2_t); return __builtin_bit_cast(unsigned, r); }
; DI f32x16 mfma32(bf16x8 a, bf16x8 b, f32x16 c) { return __builtin_amdgcn_mfma_f32_32x32x16_bf16(a, b, c, 0, 0, 0); }
;     ...
;   const float mn = fmaxf(m, mx); const float alpha = __builtin_amdgcn_exp2f(m - mn);
;   const float neg = (MODE == 2 && !lanesel) ? NINF : -mn;
;   float ps = 0.f;
; #pragma unroll
;   for (int k2 = 0; k2 < 2; ++k2)
; #pragma unroll
;     for (int i = 0; i < 16; ++i) {
;       if (!(HM & (1 << k2))) continue;
;       const float pv = (MODE == 1) ? __builtin_amdgcn_exp2f(s[k2][i] + neg) : __builtin_amdgcn_exp2f(fmaf(s[k2][i], L2E, neg));
;       s[k2][i] = pv; ps += pv;
;     }
;   l = l * alpha + ps;
;   if (__builtin_amdgcn_ballot_w64(mn != m) != 0ull) {
; #pragma unroll
;     for (int dt = 0; dt < 2; ++dt)
; #pragma unroll
;       for (int i = 0; i < 16; ++i) o[dt][i] *= alpha;
;   }
;   m = mn;
; #pragma unroll
;   for (int st = 0; st < 4; ++st) {
;     if (!(HM & (1 << (st >> 1)))) continue;
;     const int k2 = st >> 1, b8 = 8 * (st & 1);
;     const u32x4 pw = {pack2(s[k2][b8], s[k2][b8 + 1]), pack2(s[k2][b8 + 2], s[k2][b8 + 3]), pack2(s[k2][b8 + 4], s[k2][b8 + 5]), pack2(s[k2][b8 + 6], s[k2][b8 + 7])};
;     const bf16x8 pb = __builtin_bit_cast(bf16x8, pw);
; #pragma unroll
;     for (int dt = 0; dt < 2; ++dt) {
;       const s16x4 lo = *(const s16x4*)(Vs + (32 * dt + r) * LSTR + 16 * st + 4 * h);
;       const s16x4 hi = *(const s16x4*)(Vs + (32 * dt + r) * LSTR + 16 * st + 8 + 4 * h);
;       const bf16x8 a = __builtin_shufflevector(lo, hi, 0, 1, 2, 3, 4, 5, 6, 7);
;       o[dt] = mfma32(a, pb, o[dt]);
;     }
;   }
.LBB0_788:
	v_sub_f32_e32 v136, v211, v192
	v_exp_f32_e32 v136, v136
	v_sub_f32_e32 v210, v210, v192
	v_exp_f32_e32 v210, v210
	v_sub_f32_e32 v209, v209, v192
	v_exp_f32_e32 v209, v209
	v_sub_f32_e32 v163, v163, v192
	v_exp_f32_e32 v163, v163
	v_sub_f32_e32 v194, v194, v192
	v_add_f32_e32 v140, 0, v136
	v_exp_f32_e32 v211, v194
	v_sub_f32_e32 v162, v162, v192
	v_add_f32_e32 v140, v210, v140
	v_exp_f32_e32 v162, v162
	v_sub_f32_e32 v161, v161, v192
	v_add_f32_e32 v140, v209, v140
	v_exp_f32_e32 v161, v161
	v_sub_f32_e32 v159, v159, v192
	v_add_f32_e32 v140, v163, v140
	v_exp_f32_e32 v159, v159
	v_sub_f32_e32 v160, v160, v192
	v_add_f32_e32 v140, v211, v140
	v_exp_f32_e32 v160, v160
	v_sub_f32_e32 v158, v158, v192
	v_add_f32_e32 v140, v162, v140
	v_exp_f32_e32 v158, v158
	v_sub_f32_e32 v157, v157, v192
	v_add_f32_e32 v140, v161, v140
	v_exp_f32_e32 v157, v157
	v_sub_f32_e32 v155, v155, v192
	v_add_f32_e32 v140, v159, v140
	v_exp_f32_e32 v155, v155
	v_sub_f32_e32 v156, v156, v192
	v_add_f32_e32 v140, v160, v140
	v_exp_f32_e32 v156, v156
	v_sub_f32_e32 v154, v154, v192
	v_add_f32_e32 v140, v158, v140
	v_exp_f32_e32 v154, v154
	v_sub_f32_e32 v152, v152, v192
	v_add_f32_e32 v140, v157, v140
	v_exp_f32_e32 v152, v152
	v_sub_f32_e32 v153, v153, v192
	v_add_f32_e32 v140, v155, v140
	v_exp_f32_e32 v153, v153
	v_sub_f32_e32 v151, v151, v192
	v_add_f32_e32 v140, v156, v140
	v_exp_f32_e32 v151, v151
	v_sub_f32_e32 v150, v150, v192
	v_add_f32_e32 v140, v154, v140
	v_exp_f32_e32 v150, v150
	v_sub_f32_e32 v148, v148, v192
	v_add_f32_e32 v140, v152, v140
	v_exp_f32_e32 v148, v148
	v_sub_f32_e32 v149, v149, v192
	v_add_f32_e32 v140, v153, v140
	v_exp_f32_e32 v149, v149
	v_sub_f32_e32 v147, v147, v192
	v_add_f32_e32 v140, v151, v140
	v_exp_f32_e32 v147, v147
	v_sub_f32_e32 v146, v146, v192
	v_add_f32_e32 v140, v150, v140
	v_exp_f32_e32 v146, v146
	v_sub_f32_e32 v142, v142, v192
	v_add_f32_e32 v140, v148, v140
	v_exp_f32_e32 v212, v142
	v_sub_f32_e32 v142, v145, v192
	v_add_f32_e32 v140, v149, v140
	v_exp_f32_e32 v213, v142
	v_sub_f32_e32 v142, v144, v192
	v_add_f32_e32 v140, v147, v140
	v_exp_f32_e32 v214, v142
	v_sub_f32_e32 v142, v143, v192
	v_add_f32_e32 v140, v146, v140
	v_exp_f32_e32 v215, v142
	v_sub_f32_e32 v139, v139, v192
	v_add_f32_e32 v140, v212, v140
	v_exp_f32_e32 v216, v139
	v_add_f32_e32 v140, v213, v140
	v_add_f32_e32 v140, v214, v140
	v_add_f32_e32 v140, v215, v140
	v_add_f32_e32 v139, v216, v140
	v_sub_f32_e32 v140, v141, v192
	v_exp_f32_e32 v217, v140
	v_sub_f32_e32 v138, v138, v192
	v_exp_f32_e32 v218, v138
	v_sub_f32_e32 v135, v135, v192
	v_exp_f32_e32 v219, v135
	v_sub_f32_e32 v134, v134, v192
	v_exp_f32_e32 v220, v134
	v_add_f32_e32 v139, v217, v139
	v_add_f32_e32 v138, v218, v139
	v_add_f32_e32 v135, v219, v138
	v_add_f32_e32 v134, v220, v135
	v_sub_f32_e32 v135, v137, v192
	v_exp_f32_e32 v221, v135
	v_cvt_pk_bf16_f32 v135, v209, v163
	v_cvt_pk_bf16_f32 v137, v161, v159
	v_add_u32_e32 v159, 0x3000, v198
	v_add_f32_e32 v194, v221, v134
	v_fmac_f32_e32 v194, v193, v0
	v_add_u32_e32 v0, 0x2000, v198
	v_add_u32_e32 v242, 0x3000, v198
	ds_read2_b64 v[138:141], v0 offset0:128 offset1:130
	ds_read2_b64 v[142:145], v0 offset0:132 offset1:134
	ds_read2_b64 v[234:237], v242 offset0:192 offset1:194
	ds_read2_b64 v[238:241], v242 offset0:196 offset1:198
	v_cvt_pk_bf16_f32 v134, v136, v210
	v_cvt_pk_bf16_f32 v136, v211, v162
	s_mov_b64 s[8:9], 0
	s_waitcnt lgkmcnt(3)
	v_mfma_f32_32x32x16_bf16 v[34:49], v[138:141], v[134:137], v[2:17]
	ds_read2_b64 v[138:141], v0 offset0:136 offset1:138
	s_waitcnt lgkmcnt(2)
	v_mfma_f32_32x32x16_bf16 v[50:65], v[234:237], v[134:137], v[18:33]
	ds_read2_b64 v[234:237], v242 offset0:200 offset1:202
	v_cvt_pk_bf16_f32 v134, v160, v158
	v_cvt_pk_bf16_f32 v135, v157, v155
	v_cvt_pk_bf16_f32 v136, v156, v154
	v_cvt_pk_bf16_f32 v137, v152, v153
	s_waitcnt lgkmcnt(2)
	s_nop 0
	v_mfma_f32_32x32x16_bf16 v[50:65], v[238:241], v[134:137], v[50:65]
	ds_read2_b64 v[238:241], v0 offset0:140 offset1:142
	v_mfma_f32_32x32x16_bf16 v[34:49], v[142:145], v[134:137], v[34:49]
	ds_read2_b64 v[142:145], v242 offset0:204 offset1:206
	v_cvt_pk_bf16_f32 v134, v151, v150
	v_cvt_pk_bf16_f32 v135, v148, v149
	v_cvt_pk_bf16_f32 v136, v147, v146
	v_cvt_pk_bf16_f32 v137, v212, v213
	s_waitcnt lgkmcnt(3)
	s_nop 0
	v_mfma_f32_32x32x16_bf16 v[34:49], v[138:141], v[134:137], v[34:49]
	s_waitcnt lgkmcnt(2)
	v_mfma_f32_32x32x16_bf16 v[50:65], v[234:237], v[134:137], v[50:65]
	v_cvt_pk_bf16_f32 v134, v214, v215
	v_cvt_pk_bf16_f32 v135, v216, v217
	v_cvt_pk_bf16_f32 v136, v218, v219
	v_cvt_pk_bf16_f32 v137, v220, v221
	s_waitcnt lgkmcnt(1)
	s_nop 0
	v_mfma_f32_32x32x16_bf16 v[2:17], v[238:241], v[134:137], v[34:49]
	s_waitcnt lgkmcnt(0)
	v_mfma_f32_32x32x16_bf16 v[18:33], v[142:145], v[134:137], v[50:65]

; DI unsigned pack2(float a, float b) { f32x2 v = {a, b}; bf16x2_t r = __builtin_convertvector(v, bf16x2_t); return __builtin_bit_cast(unsigned, r); }
; DI f32x16 mfma32(bf16x8 a, bf16x8 b, f32x16 c) { return __builtin_amdgcn_mfma_f32_32x32x16_bf16(a, b, c, 0, 0, 0); }
;     ...
;   const float mn = fmaxf(m, mx); const float alpha = __builtin_amdgcn_exp2f(m - mn);
;   const float neg = (MODE == 2 && !lanesel) ? NINF : -mn;
;   float ps = 0.f;
; #pragma unroll
;   for (int k2 = 0; k2 < 2; ++k2)
; #pragma unroll
;     for (int i = 0; i < 16; ++i) {
;       if (!(HM & (1 << k2))) continue;
;       const float pv = (MODE == 1) ? __builtin_amdgcn_exp2f(s[k2][i] + neg) : __builtin_amdgcn_exp2f(fmaf(s[k2][i], L2E, neg));
;       s[k2][i] = pv; ps += pv;
;     }
;   l = l * alpha + ps;
;   if (__builtin_amdgcn_ballot_w64(mn != m) != 0ull) {
; #pragma unroll
;     for (int dt = 0; dt < 2; ++dt)
; #pragma unroll
;       for (int i = 0; i < 16; ++i) o[dt][i] *= alpha;
;   }
;   m = mn;
; #pragma unroll
;   for (int st = 0; st < 4; ++st) {
;     if (!(HM & (1 << (st >> 1)))) continue;
;     const int k2 = st >> 1, b8 = 8 * (st & 1);
;     const u32x4 pw = {pack2(s[k2][b8], s[k2][b8 + 1]), pack2(s[k2][b8 + 2], s[k2][b8 + 3]), pack2(s[k2][b8 + 4], s[k2][b8 + 5]), pack2(s[k2][b8 + 6], s[k2][b8 + 7])};
;     const bf16x8 pb = __builtin_bit_cast(bf16x8, pw);
; #pragma unroll
;     for (int dt = 0; dt < 2; ++dt) {
;       const s16x4 lo = *(const s16x4*)(Vs + (32 * dt + r) * LSTR + 16 * st + 4 * h);
;       const s16x4 hi = *(const s16x4*)(Vs + (32 * dt + r) * LSTR + 16 * st + 8 + 4 * h);
;       const bf16x8 a = __builtin_shufflevector(lo, hi, 0, 1, 2, 3, 4, 5, 6, 7);
;       o[dt] = mfma32(a, pb, o[dt]);
;     }
;   }
.LBB0_802:
	v_sub_f32_e32 v136, v211, v191
	v_exp_f32_e32 v136, v136
	v_sub_f32_e32 v210, v210, v191
	v_exp_f32_e32 v210, v210
	v_sub_f32_e32 v209, v209, v191
	v_exp_f32_e32 v209, v209
	v_sub_f32_e32 v163, v163, v191
	v_exp_f32_e32 v163, v163
	v_sub_f32_e32 v193, v193, v191
	v_add_f32_e32 v140, 0, v136
	v_exp_f32_e32 v211, v193
	v_sub_f32_e32 v162, v162, v191
	v_add_f32_e32 v140, v210, v140
	v_exp_f32_e32 v162, v162
	v_sub_f32_e32 v161, v161, v191
	v_add_f32_e32 v140, v209, v140
	v_exp_f32_e32 v161, v161
	v_sub_f32_e32 v159, v159, v191
	v_add_f32_e32 v140, v163, v140
	v_exp_f32_e32 v159, v159
	v_sub_f32_e32 v160, v160, v191
	v_add_f32_e32 v140, v211, v140
	v_exp_f32_e32 v160, v160
	v_sub_f32_e32 v158, v158, v191
	v_add_f32_e32 v140, v162, v140
	v_exp_f32_e32 v158, v158
	v_sub_f32_e32 v157, v157, v191
	v_add_f32_e32 v140, v161, v140
	v_exp_f32_e32 v157, v157
	v_sub_f32_e32 v155, v155, v191
	v_add_f32_e32 v140, v159, v140
	v_exp_f32_e32 v155, v155
	v_sub_f32_e32 v156, v156, v191
	v_add_f32_e32 v140, v160, v140
	v_exp_f32_e32 v156, v156
	v_sub_f32_e32 v154, v154, v191
	v_add_f32_e32 v140, v158, v140
	v_exp_f32_e32 v154, v154
	v_sub_f32_e32 v152, v152, v191
	v_add_f32_e32 v140, v157, v140
	v_exp_f32_e32 v152, v152
	v_sub_f32_e32 v153, v153, v191
	v_add_f32_e32 v140, v155, v140
	v_exp_f32_e32 v153, v153
	v_sub_f32_e32 v151, v151, v191
	v_add_f32_e32 v140, v156, v140
	v_exp_f32_e32 v151, v151
	v_sub_f32_e32 v150, v150, v191
	v_add_f32_e32 v140, v154, v140
	v_exp_f32_e32 v150, v150
	v_sub_f32_e32 v148, v148, v191
	v_add_f32_e32 v140, v152, v140
	v_exp_f32_e32 v148, v148
	v_sub_f32_e32 v149, v149, v191
	v_add_f32_e32 v140, v153, v140
	v_exp_f32_e32 v149, v149
	v_sub_f32_e32 v147, v147, v191
	v_add_f32_e32 v140, v151, v140
	v_exp_f32_e32 v147, v147
	v_sub_f32_e32 v146, v146, v191
	v_add_f32_e32 v140, v150, v140
	v_exp_f32_e32 v146, v146
	v_sub_f32_e32 v142, v142, v191
	v_add_f32_e32 v140, v148, v140
	v_exp_f32_e32 v212, v142
	v_sub_f32_e32 v142, v145, v191
	v_add_f32_e32 v140, v149, v140
	v_exp_f32_e32 v213, v142
	v_sub_f32_e32 v142, v144, v191
	v_add_f32_e32 v140, v147, v140
	v_exp_f32_e32 v214, v142
	v_sub_f32_e32 v142, v143, v191
	v_add_f32_e32 v140, v146, v140
	v_exp_f32_e32 v215, v142
	v_sub_f32_e32 v139, v139, v191
	v_add_f32_e32 v140, v212, v140
	v_exp_f32_e32 v216, v139
	v_add_f32_e32 v140, v213, v140
	v_add_f32_e32 v140, v214, v140
	v_add_f32_e32 v140, v215, v140
	v_add_f32_e32 v139, v216, v140
	v_sub_f32_e32 v140, v141, v191
	v_exp_f32_e32 v217, v140
	v_sub_f32_e32 v138, v138, v191
	v_exp_f32_e32 v218, v138
	v_sub_f32_e32 v135, v135, v191
	v_exp_f32_e32 v219, v135
	v_sub_f32_e32 v134, v134, v191
	v_exp_f32_e32 v220, v134
	v_add_f32_e32 v139, v217, v139
	v_add_f32_e32 v138, v218, v139
	v_add_f32_e32 v135, v219, v138
	v_add_f32_e32 v134, v220, v135
	v_sub_f32_e32 v135, v137, v191
	v_exp_f32_e32 v221, v135
	v_cvt_pk_bf16_f32 v135, v209, v163
	v_cvt_pk_bf16_f32 v137, v161, v159
	v_add_u32_e32 v159, 0x7800, v198
	v_add_f32_e32 v193, v221, v134
	v_fmac_f32_e32 v193, v194, v0
	v_add_u32_e32 v0, 0x6800, v198
	v_add_u32_e32 v242, 0x7800, v198
	ds_read2_b64 v[138:141], v0 offset0:128 offset1:130
	ds_read2_b64 v[142:145], v0 offset0:132 offset1:134
	ds_read2_b64 v[234:237], v242 offset0:192 offset1:194
	ds_read2_b64 v[238:241], v242 offset0:196 offset1:198
	v_cvt_pk_bf16_f32 v134, v136, v210
	v_cvt_pk_bf16_f32 v136, v211, v162
	s_mov_b64 s[8:9], 0
	s_waitcnt lgkmcnt(3)
	v_mfma_f32_32x32x16_bf16 v[34:49], v[138:141], v[134:137], v[2:17]
	ds_read2_b64 v[138:141], v0 offset0:136 offset1:138
	s_waitcnt lgkmcnt(2)
	v_mfma_f32_32x32x16_bf16 v[50:65], v[234:237], v[134:137], v[18:33]
	ds_read2_b64 v[234:237], v242 offset0:200 offset1:202
	v_cvt_pk_bf16_f32 v134, v160, v158
	v_cvt_pk_bf16_f32 v135, v157, v155
	v_cvt_pk_bf16_f32 v136, v156, v154
	v_cvt_pk_bf16_f32 v137, v152, v153
	s_waitcnt lgkmcnt(2)
	s_nop 0
	v_mfma_f32_32x32x16_bf16 v[50:65], v[238:241], v[134:137], v[50:65]
	ds_read2_b64 v[238:241], v0 offset0:140 offset1:142
	v_mfma_f32_32x32x16_bf16 v[34:49], v[142:145], v[134:137], v[34:49]
	ds_read2_b64 v[142:145], v242 offset0:204 offset1:206
	v_cvt_pk_bf16_f32 v134, v151, v150
	v_cvt_pk_bf16_f32 v135, v148, v149
	v_cvt_pk_bf16_f32 v136, v147, v146
	v_cvt_pk_bf16_f32 v137, v212, v213
	s_waitcnt lgkmcnt(3)
	s_nop 0
	v_mfma_f32_32x32x16_bf16 v[34:49], v[138:141], v[134:137], v[34:49]
	s_waitcnt lgkmcnt(2)
	v_mfma_f32_32x32x16_bf16 v[50:65], v[234:237], v[134:137], v[50:65]
	v_cvt_pk_bf16_f32 v134, v214, v215
	v_cvt_pk_bf16_f32 v135, v216, v217
	v_cvt_pk_bf16_f32 v136, v218, v219
	v_cvt_pk_bf16_f32 v137, v220, v221
	s_waitcnt lgkmcnt(1)
	s_nop 0
	v_mfma_f32_32x32x16_bf16 v[2:17], v[238:241], v[134:137], v[34:49]
	s_waitcnt lgkmcnt(0)
	v_mfma_f32_32x32x16_bf16 v[18:33], v[142:145], v[134:137], v[50:65]

; DI unsigned pack2(float a, float b) { f32x2 v = {a, b}; bf16x2_t r = __builtin_convertvector(v, bf16x2_t); return __builtin_bit_cast(unsigned, r); }
; DI f32x16 mfma32(bf16x8 a, bf16x8 b, f32x16 c) { return __builtin_amdgcn_mfma_f32_32x32x16_bf16(a, b, c, 0, 0, 0); }
;     ...
;   const float mn = fmaxf(m, mx); const float alpha = __builtin_amdgcn_exp2f(m - mn);
;   const float neg = (MODE == 2 && !lanesel) ? NINF : -mn;
;   float ps = 0.f;
; #pragma unroll
;   for (int k2 = 0; k2 < 2; ++k2)
; #pragma unroll
;     for (int i = 0; i < 16; ++i) {
;       if (!(HM & (1 << k2))) continue;
;       const float pv = (MODE == 1) ? __builtin_amdgcn_exp2f(s[k2][i] + neg) : __builtin_amdgcn_exp2f(fmaf(s[k2][i], L2E, neg));
;       s[k2][i] = pv; ps += pv;
;     }
;   l = l * alpha + ps;
;   if (__builtin_amdgcn_ballot_w64(mn != m) != 0ull) {
; #pragma unroll
;     for (int dt = 0; dt < 2; ++dt)
; #pragma unroll
;       for (int i = 0; i < 16; ++i) o[dt][i] *= alpha;
;   }
;   m = mn;
; #pragma unroll
;   for (int st = 0; st < 4; ++st) {
;     if (!(HM & (1 << (st >> 1)))) continue;
;     const int k2 = st >> 1, b8 = 8 * (st & 1);
;     const u32x4 pw = {pack2(s[k2][b8], s[k2][b8 + 1]), pack2(s[k2][b8 + 2], s[k2][b8 + 3]), pack2(s[k2][b8 + 4], s[k2][b8 + 5]), pack2(s[k2][b8 + 6], s[k2][b8 + 7])};
;     const bf16x8 pb = __builtin_bit_cast(bf16x8, pw);
; #pragma unroll
;     for (int dt = 0; dt < 2; ++dt) {
;       const s16x4 lo = *(const s16x4*)(Vs + (32 * dt + r) * LSTR + 16 * st + 4 * h);
;       const s16x4 hi = *(const s16x4*)(Vs + (32 * dt + r) * LSTR + 16 * st + 8 + 4 * h);
;       const bf16x8 a = __builtin_shufflevector(lo, hi, 0, 1, 2, 3, 4, 5, 6, 7);
;       o[dt] = mfma32(a, pb, o[dt]);
;     }
;   }
.LBB0_827:
	v_cndmask_b32_e64 v214, -v212, v204, s[6:7]
	v_fmamk_f32 v82, v82, 0x3fb8aa3b, v214
	v_exp_f32_e32 v82, v82
	v_fmamk_f32 v83, v83, 0x3fb8aa3b, v214
	v_exp_f32_e32 v83, v83
	v_fmamk_f32 v84, v84, 0x3fb8aa3b, v214
	v_exp_f32_e32 v84, v84
	v_fmamk_f32 v85, v85, 0x3fb8aa3b, v214
	v_exp_f32_e32 v85, v85
	v_fmamk_f32 v86, v86, 0x3fb8aa3b, v214
	v_add_f32_e32 v217, 0, v82
	v_exp_f32_e32 v86, v86
	v_fmamk_f32 v87, v87, 0x3fb8aa3b, v214
	v_add_f32_e32 v217, v83, v217
	v_exp_f32_e32 v87, v87
	v_fmamk_f32 v88, v88, 0x3fb8aa3b, v214
	v_add_f32_e32 v217, v84, v217
	v_exp_f32_e32 v88, v88
	v_fmamk_f32 v89, v89, 0x3fb8aa3b, v214
	v_add_f32_e32 v217, v85, v217
	v_exp_f32_e32 v89, v89
	v_fmamk_f32 v90, v90, 0x3fb8aa3b, v214
	v_add_f32_e32 v217, v86, v217
	v_exp_f32_e32 v90, v90
	v_fmamk_f32 v91, v91, 0x3fb8aa3b, v214
	v_add_f32_e32 v217, v87, v217
	v_exp_f32_e32 v91, v91
	v_fmamk_f32 v92, v92, 0x3fb8aa3b, v214
	v_add_f32_e32 v217, v88, v217
	v_exp_f32_e32 v92, v92
	v_fmamk_f32 v93, v93, 0x3fb8aa3b, v214
	v_add_f32_e32 v217, v89, v217
	v_exp_f32_e32 v93, v93
	v_fmamk_f32 v94, v94, 0x3fb8aa3b, v214
	v_add_f32_e32 v217, v90, v217
	v_exp_f32_e32 v94, v94
	v_fmamk_f32 v95, v95, 0x3fb8aa3b, v214
	v_add_f32_e32 v217, v91, v217
	v_exp_f32_e32 v95, v95
	v_fmamk_f32 v96, v96, 0x3fb8aa3b, v214
	v_add_f32_e32 v217, v92, v217
	v_exp_f32_e32 v96, v96
	v_fmamk_f32 v97, v97, 0x3fb8aa3b, v214
	v_add_f32_e32 v217, v93, v217
	v_exp_f32_e32 v97, v97
	v_fmamk_f32 v66, v66, 0x3fb8aa3b, v214
	v_add_f32_e32 v217, v94, v217
	v_exp_f32_e32 v218, v66
	v_add_f32_e32 v217, v95, v217
	v_add_f32_e32 v217, v96, v217
	v_add_f32_e32 v217, v97, v217
	v_fmamk_f32 v67, v67, 0x3fb8aa3b, v214
	v_add_f32_e32 v66, v218, v217
	v_exp_f32_e32 v217, v67
	v_fmamk_f32 v67, v68, 0x3fb8aa3b, v214
	v_exp_f32_e32 v219, v67
	v_fmamk_f32 v67, v69, 0x3fb8aa3b, v214
	v_exp_f32_e32 v220, v67
	v_fmamk_f32 v67, v70, 0x3fb8aa3b, v214
	v_exp_f32_e32 v221, v67
	v_fmamk_f32 v67, v71, 0x3fb8aa3b, v214
	v_add_f32_e32 v66, v217, v66
	v_exp_f32_e32 v222, v67
	v_fmamk_f32 v67, v72, 0x3fb8aa3b, v214
	v_add_f32_e32 v66, v219, v66
	v_exp_f32_e32 v223, v67
	v_fmamk_f32 v67, v73, 0x3fb8aa3b, v214
	v_add_f32_e32 v66, v220, v66
	v_exp_f32_e32 v224, v67
	v_fmamk_f32 v67, v74, 0x3fb8aa3b, v214
	v_add_f32_e32 v66, v221, v66
	v_exp_f32_e32 v225, v67
	v_fmamk_f32 v67, v75, 0x3fb8aa3b, v214
	v_add_f32_e32 v66, v222, v66
	v_exp_f32_e32 v226, v67
	v_fmamk_f32 v67, v76, 0x3fb8aa3b, v214
	v_add_f32_e32 v66, v223, v66
	v_exp_f32_e32 v227, v67
	v_fmamk_f32 v67, v77, 0x3fb8aa3b, v214
	v_add_f32_e32 v66, v224, v66
	v_exp_f32_e32 v228, v67
	v_fmamk_f32 v67, v78, 0x3fb8aa3b, v214
	v_add_f32_e32 v66, v225, v66
	v_exp_f32_e32 v78, v67
	v_fmamk_f32 v67, v79, 0x3fb8aa3b, v214
	v_add_f32_e32 v66, v226, v66
	v_exp_f32_e32 v79, v67
	v_fmamk_f32 v67, v80, 0x3fb8aa3b, v214
	v_add_f32_e32 v66, v227, v66
	v_exp_f32_e32 v80, v67
	v_fmac_f32_e32 v214, 0x3fb8aa3b, v81
	v_add_f32_e32 v66, v228, v66
	v_exp_f32_e32 v81, v214
	v_add_f32_e32 v66, v78, v66
	v_add_f32_e32 v66, v79, v66
	v_add_f32_e32 v66, v80, v66
	v_add_f32_e32 v214, v81, v66
	v_fmac_f32_e32 v214, v213, v0
	v_add_u32_e32 v0, 0x2000, v198
	v_add_u32_e32 v242, 0x3000, v198
	ds_read2_b64 v[70:73], v0 offset0:128 offset1:130
	ds_read2_b64 v[74:77], v0 offset0:132 offset1:134
	ds_read2_b64 v[234:237], v242 offset0:192 offset1:194
	ds_read2_b64 v[238:241], v242 offset0:196 offset1:198
	v_cvt_pk_bf16_f32 v66, v82, v83
	v_cvt_pk_bf16_f32 v67, v84, v85
	v_cvt_pk_bf16_f32 v68, v86, v87
	v_cvt_pk_bf16_f32 v69, v88, v89
	v_add_u32_e32 v82, 0x3000, v198
	s_mov_b64 s[8:9], 0
	s_waitcnt lgkmcnt(3)
	v_mfma_f32_32x32x16_bf16 v[34:49], v[70:73], v[66:69], v[2:17]
	ds_read2_b64 v[70:73], v0 offset0:136 offset1:138
	s_waitcnt lgkmcnt(2)
	v_mfma_f32_32x32x16_bf16 v[50:65], v[234:237], v[66:69], v[18:33]
	ds_read2_b64 v[234:237], v242 offset0:200 offset1:202
	v_cvt_pk_bf16_f32 v66, v90, v91
	v_cvt_pk_bf16_f32 v67, v92, v93
	v_cvt_pk_bf16_f32 v68, v94, v95
	v_cvt_pk_bf16_f32 v69, v96, v97
	s_waitcnt lgkmcnt(2)
	s_nop 0
	v_mfma_f32_32x32x16_bf16 v[50:65], v[238:241], v[66:69], v[50:65]
	ds_read2_b64 v[238:241], v0 offset0:140 offset1:142
	v_mfma_f32_32x32x16_bf16 v[34:49], v[74:77], v[66:69], v[34:49]
	ds_read2_b64 v[74:77], v242 offset0:204 offset1:206
	v_cvt_pk_bf16_f32 v66, v218, v217
	v_cvt_pk_bf16_f32 v67, v219, v220
	v_cvt_pk_bf16_f32 v68, v221, v222
	v_cvt_pk_bf16_f32 v69, v223, v224
	s_waitcnt lgkmcnt(3)
	s_nop 0
	v_mfma_f32_32x32x16_bf16 v[34:49], v[70:73], v[66:69], v[34:49]
	s_waitcnt lgkmcnt(2)
	v_mfma_f32_32x32x16_bf16 v[50:65], v[234:237], v[66:69], v[50:65]
	v_cvt_pk_bf16_f32 v66, v225, v226
	v_cvt_pk_bf16_f32 v67, v227, v228
	v_cvt_pk_bf16_f32 v68, v78, v79
	v_cvt_pk_bf16_f32 v69, v80, v81
	s_waitcnt lgkmcnt(1)
	s_nop 0
	v_mfma_f32_32x32x16_bf16 v[2:17], v[238:241], v[66:69], v[34:49]
	s_waitcnt lgkmcnt(0)
	v_mfma_f32_32x32x16_bf16 v[18:33], v[74:77], v[66:69], v[50:65]

; DI unsigned pack2(float a, float b) { f32x2 v = {a, b}; bf16x2_t r = __builtin_convertvector(v, bf16x2_t); return __builtin_bit_cast(unsigned, r); }
; DI f32x16 mfma32(bf16x8 a, bf16x8 b, f32x16 c) { return __builtin_amdgcn_mfma_f32_32x32x16_bf16(a, b, c, 0, 0, 0); }
;     ...
;   const float mn = fmaxf(m, mx); const float alpha = __builtin_amdgcn_exp2f(m - mn);
;   const float neg = (MODE == 2 && !lanesel) ? NINF : -mn;
;   float ps = 0.f;
; #pragma unroll
;   for (int k2 = 0; k2 < 2; ++k2)
; #pragma unroll
;     for (int i = 0; i < 16; ++i) {
;       if (!(HM & (1 << k2))) continue;
;       const float pv = (MODE == 1) ? __builtin_amdgcn_exp2f(s[k2][i] + neg) : __builtin_amdgcn_exp2f(fmaf(s[k2][i], L2E, neg));
;       s[k2][i] = pv; ps += pv;
;     }
;   l = l * alpha + ps;
;   if (__builtin_amdgcn_ballot_w64(mn != m) != 0ull) {
; #pragma unroll
;     for (int dt = 0; dt < 2; ++dt)
; #pragma unroll
;       for (int i = 0; i < 16; ++i) o[dt][i] *= alpha;
;   }
;   m = mn;
; #pragma unroll
;   for (int st = 0; st < 4; ++st) {
;     if (!(HM & (1 << (st >> 1)))) continue;
;     const int k2 = st >> 1, b8 = 8 * (st & 1);
;     const u32x4 pw = {pack2(s[k2][b8], s[k2][b8 + 1]), pack2(s[k2][b8 + 2], s[k2][b8 + 3]), pack2(s[k2][b8 + 4], s[k2][b8 + 5]), pack2(s[k2][b8 + 6], s[k2][b8 + 7])};
;     const bf16x8 pb = __builtin_bit_cast(bf16x8, pw);
; #pragma unroll
;     for (int dt = 0; dt < 2; ++dt) {
;       const s16x4 lo = *(const s16x4*)(Vs + (32 * dt + r) * LSTR + 16 * st + 4 * h);
;       const s16x4 hi = *(const s16x4*)(Vs + (32 * dt + r) * LSTR + 16 * st + 8 + 4 * h);
;       const bf16x8 a = __builtin_shufflevector(lo, hi, 0, 1, 2, 3, 4, 5, 6, 7);
;       o[dt] = mfma32(a, pb, o[dt]);
;     }
;   }
.LBB0_840:
	v_cndmask_b32_e64 v213, -v211, v204, s[6:7]
	v_fmamk_f32 v82, v82, 0x3fb8aa3b, v213
	v_exp_f32_e32 v82, v82
	v_fmamk_f32 v83, v83, 0x3fb8aa3b, v213
	v_exp_f32_e32 v83, v83
	v_fmamk_f32 v84, v84, 0x3fb8aa3b, v213
	v_exp_f32_e32 v84, v84
	v_fmamk_f32 v85, v85, 0x3fb8aa3b, v213
	v_exp_f32_e32 v85, v85
	v_fmamk_f32 v86, v86, 0x3fb8aa3b, v213
	v_add_f32_e32 v217, 0, v82
	v_exp_f32_e32 v86, v86
	v_fmamk_f32 v87, v87, 0x3fb8aa3b, v213
	v_add_f32_e32 v217, v83, v217
	v_exp_f32_e32 v87, v87
	v_fmamk_f32 v88, v88, 0x3fb8aa3b, v213
	v_add_f32_e32 v217, v84, v217
	v_exp_f32_e32 v88, v88
	v_fmamk_f32 v89, v89, 0x3fb8aa3b, v213
	v_add_f32_e32 v217, v85, v217
	v_exp_f32_e32 v89, v89
	v_fmamk_f32 v90, v90, 0x3fb8aa3b, v213
	v_add_f32_e32 v217, v86, v217
	v_exp_f32_e32 v90, v90
	v_fmamk_f32 v91, v91, 0x3fb8aa3b, v213
	v_add_f32_e32 v217, v87, v217
	v_exp_f32_e32 v91, v91
	v_fmamk_f32 v92, v92, 0x3fb8aa3b, v213
	v_add_f32_e32 v217, v88, v217
	v_exp_f32_e32 v92, v92
	v_fmamk_f32 v93, v93, 0x3fb8aa3b, v213
	v_add_f32_e32 v217, v89, v217
	v_exp_f32_e32 v93, v93
	v_fmamk_f32 v94, v94, 0x3fb8aa3b, v213
	v_add_f32_e32 v217, v90, v217
	v_exp_f32_e32 v94, v94
	v_fmamk_f32 v95, v95, 0x3fb8aa3b, v213
	v_add_f32_e32 v217, v91, v217
	v_exp_f32_e32 v95, v95
	v_fmamk_f32 v96, v96, 0x3fb8aa3b, v213
	v_add_f32_e32 v217, v92, v217
	v_exp_f32_e32 v96, v96
	v_fmamk_f32 v97, v97, 0x3fb8aa3b, v213
	v_add_f32_e32 v217, v93, v217
	v_exp_f32_e32 v97, v97
	v_fmamk_f32 v66, v66, 0x3fb8aa3b, v213
	v_add_f32_e32 v217, v94, v217
	v_exp_f32_e32 v218, v66
	v_add_f32_e32 v217, v95, v217
	v_add_f32_e32 v217, v96, v217
	v_add_f32_e32 v217, v97, v217
	v_fmamk_f32 v67, v67, 0x3fb8aa3b, v213
	v_add_f32_e32 v66, v218, v217
	v_exp_f32_e32 v217, v67
	v_fmamk_f32 v67, v68, 0x3fb8aa3b, v213
	v_exp_f32_e32 v219, v67
	v_fmamk_f32 v67, v69, 0x3fb8aa3b, v213
	v_exp_f32_e32 v220, v67
	v_fmamk_f32 v67, v70, 0x3fb8aa3b, v213
	v_exp_f32_e32 v221, v67
	v_fmamk_f32 v67, v71, 0x3fb8aa3b, v213
	v_add_f32_e32 v66, v217, v66
	v_exp_f32_e32 v222, v67
	v_fmamk_f32 v67, v72, 0x3fb8aa3b, v213
	v_add_f32_e32 v66, v219, v66
	v_exp_f32_e32 v223, v67
	v_fmamk_f32 v67, v73, 0x3fb8aa3b, v213
	v_add_f32_e32 v66, v220, v66
	v_exp_f32_e32 v224, v67
	v_fmamk_f32 v67, v74, 0x3fb8aa3b, v213
	v_add_f32_e32 v66, v221, v66
	v_exp_f32_e32 v225, v67
	v_fmamk_f32 v67, v75, 0x3fb8aa3b, v213
	v_add_f32_e32 v66, v222, v66
	v_exp_f32_e32 v226, v67
	v_fmamk_f32 v67, v76, 0x3fb8aa3b, v213
	v_add_f32_e32 v66, v223, v66
	v_exp_f32_e32 v227, v67
	v_fmamk_f32 v67, v77, 0x3fb8aa3b, v213
	v_add_f32_e32 v66, v224, v66
	v_exp_f32_e32 v228, v67
	v_fmamk_f32 v67, v78, 0x3fb8aa3b, v213
	v_add_f32_e32 v66, v225, v66
	v_exp_f32_e32 v78, v67
	v_fmamk_f32 v67, v79, 0x3fb8aa3b, v213
	v_add_f32_e32 v66, v226, v66
	v_exp_f32_e32 v79, v67
	v_fmamk_f32 v67, v80, 0x3fb8aa3b, v213
	v_add_f32_e32 v66, v227, v66
	v_exp_f32_e32 v80, v67
	v_fmac_f32_e32 v213, 0x3fb8aa3b, v81
	v_add_f32_e32 v66, v228, v66
	v_exp_f32_e32 v81, v213
	v_add_f32_e32 v66, v78, v66
	v_add_f32_e32 v66, v79, v66
	v_add_f32_e32 v66, v80, v66
	v_add_f32_e32 v213, v81, v66
	v_fmac_f32_e32 v213, v214, v0
	v_add_u32_e32 v0, 0x6800, v198
	v_add_u32_e32 v242, 0x7800, v198
	ds_read2_b64 v[70:73], v0 offset0:128 offset1:130
	ds_read2_b64 v[74:77], v0 offset0:132 offset1:134
	ds_read2_b64 v[234:237], v242 offset0:192 offset1:194
	ds_read2_b64 v[238:241], v242 offset0:196 offset1:198
	v_cvt_pk_bf16_f32 v66, v82, v83
	v_cvt_pk_bf16_f32 v67, v84, v85
	v_cvt_pk_bf16_f32 v68, v86, v87
	v_cvt_pk_bf16_f32 v69, v88, v89
	v_add_u32_e32 v82, 0x7800, v198
	s_mov_b64 s[8:9], 0
	s_waitcnt lgkmcnt(3)
	v_mfma_f32_32x32x16_bf16 v[34:49], v[70:73], v[66:69], v[2:17]
	ds_read2_b64 v[70:73], v0 offset0:136 offset1:138
	s_waitcnt lgkmcnt(2)
	v_mfma_f32_32x32x16_bf16 v[50:65], v[234:237], v[66:69], v[18:33]
	ds_read2_b64 v[234:237], v242 offset0:200 offset1:202
	v_cvt_pk_bf16_f32 v66, v90, v91
	v_cvt_pk_bf16_f32 v67, v92, v93
	v_cvt_pk_bf16_f32 v68, v94, v95
	v_cvt_pk_bf16_f32 v69, v96, v97
	s_waitcnt lgkmcnt(2)
	s_nop 0
	v_mfma_f32_32x32x16_bf16 v[50:65], v[238:241], v[66:69], v[50:65]
	ds_read2_b64 v[238:241], v0 offset0:140 offset1:142
	v_mfma_f32_32x32x16_bf16 v[34:49], v[74:77], v[66:69], v[34:49]
	ds_read2_b64 v[74:77], v242 offset0:204 offset1:206
	v_cvt_pk_bf16_f32 v66, v218, v217
	v_cvt_pk_bf16_f32 v67, v219, v220
	v_cvt_pk_bf16_f32 v68, v221, v222
	v_cvt_pk_bf16_f32 v69, v223, v224
	s_waitcnt lgkmcnt(3)
	s_nop 0
	v_mfma_f32_32x32x16_bf16 v[34:49], v[70:73], v[66:69], v[34:49]
	s_waitcnt lgkmcnt(2)
	v_mfma_f32_32x32x16_bf16 v[50:65], v[234:237], v[66:69], v[50:65]
	v_cvt_pk_bf16_f32 v66, v225, v226
	v_cvt_pk_bf16_f32 v67, v227, v228
	v_cvt_pk_bf16_f32 v68, v78, v79
	v_cvt_pk_bf16_f32 v69, v80, v81
	s_waitcnt lgkmcnt(1)
	s_nop 0
	v_mfma_f32_32x32x16_bf16 v[2:17], v[238:241], v[66:69], v[34:49]
	s_waitcnt lgkmcnt(0)
	v_mfma_f32_32x32x16_bf16 v[18:33], v[74:77], v[66:69], v[50:65]

; DI unsigned pack2(float a, float b) { f32x2 v = {a, b}; bf16x2_t r = __builtin_convertvector(v, bf16x2_t); return __builtin_bit_cast(unsigned, r); }
; DI f32x16 mfma32(bf16x8 a, bf16x8 b, f32x16 c) { return __builtin_amdgcn_mfma_f32_32x32x16_bf16(a, b, c, 0, 0, 0); }
;     ...
;   const float mn = fmaxf(m, mx); const float alpha = __builtin_amdgcn_exp2f(m - mn);
;   const float neg = (MODE == 2 && !lanesel) ? NINF : -mn;
;   float ps = 0.f;
; #pragma unroll
;   for (int k2 = 0; k2 < 2; ++k2)
; #pragma unroll
;     for (int i = 0; i < 16; ++i) {
;       if (!(HM & (1 << k2))) continue;
;       const float pv = (MODE == 1) ? __builtin_amdgcn_exp2f(s[k2][i] + neg) : __builtin_amdgcn_exp2f(fmaf(s[k2][i], L2E, neg));
;       s[k2][i] = pv; ps += pv;
;     }
;   l = l * alpha + ps;
;   if (__builtin_amdgcn_ballot_w64(mn != m) != 0ull) {
; #pragma unroll
;     for (int dt = 0; dt < 2; ++dt)
; #pragma unroll
;       for (int i = 0; i < 16; ++i) o[dt][i] *= alpha;
;   }
;   m = mn;
; #pragma unroll
;   for (int st = 0; st < 4; ++st) {
;     if (!(HM & (1 << (st >> 1)))) continue;
;     const int k2 = st >> 1, b8 = 8 * (st & 1);
;     const u32x4 pw = {pack2(s[k2][b8], s[k2][b8 + 1]), pack2(s[k2][b8 + 2], s[k2][b8 + 3]), pack2(s[k2][b8 + 4], s[k2][b8 + 5]), pack2(s[k2][b8 + 6], s[k2][b8 + 7])};
;     const bf16x8 pb = __builtin_bit_cast(bf16x8, pw);
; #pragma unroll
;     for (int dt = 0; dt < 2; ++dt) {
;       const s16x4 lo = *(const s16x4*)(Vs + (32 * dt + r) * LSTR + 16 * st + 4 * h);
;       const s16x4 hi = *(const s16x4*)(Vs + (32 * dt + r) * LSTR + 16 * st + 8 + 4 * h);
;       const bf16x8 a = __builtin_shufflevector(lo, hi, 0, 1, 2, 3, 4, 5, 6, 7);
;       o[dt] = mfma32(a, pb, o[dt]);
;     }
;   }
.LBB0_934:
	v_fma_f32 v86, v86, s34, -v160
	v_exp_f32_e32 v86, v86
	v_fma_f32 v87, v87, s34, -v160
	v_exp_f32_e32 v87, v87
	v_fma_f32 v88, v88, s34, -v160
	v_exp_f32_e32 v88, v88
	v_fma_f32 v89, v89, s34, -v160
	v_exp_f32_e32 v89, v89
	v_fma_f32 v90, v90, s34, -v160
	v_add_f32_e32 v209, 0, v86
	v_exp_f32_e32 v90, v90
	v_fma_f32 v194, v194, s34, -v160
	v_add_f32_e32 v209, v87, v209
	v_exp_f32_e32 v194, v194
	v_fma_f32 v193, v193, s34, -v160
	v_add_f32_e32 v209, v88, v209
	v_exp_f32_e32 v193, v193
	v_fma_f32 v195, v195, s34, -v160
	v_add_f32_e32 v209, v89, v209
	v_exp_f32_e32 v195, v195
	v_fma_f32 v190, v190, s34, -v160
	v_add_f32_e32 v209, v90, v209
	v_exp_f32_e32 v190, v190
	v_fma_f32 v192, v192, s34, -v160
	v_add_f32_e32 v209, v194, v209
	v_exp_f32_e32 v192, v192
	v_fma_f32 v191, v191, s34, -v160
	v_add_f32_e32 v209, v193, v209
	v_exp_f32_e32 v191, v191
	v_fma_f32 v189, v189, s34, -v160
	v_add_f32_e32 v209, v195, v209
	v_exp_f32_e32 v189, v189
	v_fma_f32 v188, v188, s34, -v160
	v_add_f32_e32 v209, v190, v209
	v_exp_f32_e32 v188, v188
	v_fma_f32 v187, v187, s34, -v160
	v_add_f32_e32 v209, v192, v209
	v_exp_f32_e32 v187, v187
	v_fma_f32 v186, v186, s34, -v160
	v_add_f32_e32 v209, v191, v209
	v_exp_f32_e32 v186, v186
	v_fma_f32 v184, v184, s34, -v160
	v_add_f32_e32 v209, v189, v209
	v_exp_f32_e32 v184, v184
	v_fma_f32 v180, v180, s34, -v160
	v_add_f32_e32 v209, v188, v209
	v_exp_f32_e32 v180, v180
	v_fma_f32 v164, v164, s34, -v160
	v_add_f32_e32 v209, v187, v209
	v_exp_f32_e32 v164, v164
	v_fma_f32 v162, v162, s34, -v160
	v_add_f32_e32 v209, v186, v209
	v_exp_f32_e32 v210, v162
	v_add_f32_e32 v209, v184, v209
	v_add_f32_e32 v209, v180, v209
	v_add_f32_e32 v209, v164, v209
	v_fma_f32 v97, v97, s34, -v160
	v_add_f32_e32 v162, v210, v209
	v_exp_f32_e32 v209, v97
	v_fma_f32 v92, v92, s34, -v160
	v_exp_f32_e32 v211, v92
	v_fma_f32 v91, v91, s34, -v160
	v_exp_f32_e32 v212, v91
	v_add_f32_e32 v97, v209, v162
	v_add_f32_e32 v92, v211, v97
	v_cvt_pk_bf16_f32 v86, v86, v87
	v_add_f32_e32 v91, v212, v92
	v_fma_f32 v92, v93, s34, -v160
	v_exp_f32_e32 v213, v92
	v_fma_f32 v92, v94, s34, -v160
	v_exp_f32_e32 v214, v92
	v_fma_f32 v92, v95, s34, -v160
	v_exp_f32_e32 v215, v92
	v_fma_f32 v92, v96, s34, -v160
	v_exp_f32_e32 v216, v92
	v_fma_f32 v92, v163, s34, -v160
	v_add_f32_e32 v91, v213, v91
	v_exp_f32_e32 v163, v92
	v_fma_f32 v92, v165, s34, -v160
	v_add_f32_e32 v91, v214, v91
	v_exp_f32_e32 v165, v92
	v_fma_f32 v92, v181, s34, -v160
	v_add_f32_e32 v91, v215, v91
	v_exp_f32_e32 v181, v92
	v_fma_f32 v92, v182, s34, -v160
	v_add_f32_e32 v91, v216, v91
	v_exp_f32_e32 v182, v92
	v_fma_f32 v92, v183, s34, -v160
	v_add_f32_e32 v91, v163, v91
	v_exp_f32_e32 v183, v92
	v_fma_f32 v92, v185, s34, -v160
	v_add_f32_e32 v91, v165, v91
	v_exp_f32_e32 v185, v92
	v_add_f32_e32 v91, v181, v91
	v_add_f32_e32 v91, v182, v91
	v_add_f32_e32 v91, v183, v91
	v_add_f32_e32 v162, v185, v91
	v_fmac_f32_e32 v162, v161, v0
	v_add_u32_e32 v0, 0x2000, v198
	v_cvt_pk_bf16_f32 v87, v88, v89
	v_cvt_pk_bf16_f32 v88, v90, v194
	v_add_u32_e32 v242, 0x3000, v198
	ds_read2_b64 v[90:93], v0 offset0:128 offset1:130
	ds_read2_b64 v[94:97], v0 offset0:132 offset1:134
	ds_read2_b64 v[234:237], v242 offset0:192 offset1:194
	ds_read2_b64 v[238:241], v242 offset0:196 offset1:198
	v_cvt_pk_bf16_f32 v89, v193, v195
	v_add_u32_e32 v193, 0x3000, v198
	s_mov_b64 s[6:7], 0
	s_waitcnt lgkmcnt(3)
	v_mfma_f32_32x32x16_bf16 v[34:49], v[90:93], v[86:89], v[2:17]
	ds_read2_b64 v[90:93], v0 offset0:136 offset1:138
	s_waitcnt lgkmcnt(2)
	v_mfma_f32_32x32x16_bf16 v[50:65], v[234:237], v[86:89], v[18:33]
	ds_read2_b64 v[234:237], v242 offset0:200 offset1:202
	v_cvt_pk_bf16_f32 v86, v190, v192
	v_cvt_pk_bf16_f32 v87, v191, v189
	v_cvt_pk_bf16_f32 v88, v188, v187
	v_cvt_pk_bf16_f32 v89, v186, v184
	s_waitcnt lgkmcnt(2)
	s_nop 0
	v_mfma_f32_32x32x16_bf16 v[50:65], v[238:241], v[86:89], v[50:65]
	ds_read2_b64 v[238:241], v0 offset0:140 offset1:142
	v_mfma_f32_32x32x16_bf16 v[34:49], v[94:97], v[86:89], v[34:49]
	ds_read2_b64 v[94:97], v242 offset0:204 offset1:206
	v_cvt_pk_bf16_f32 v86, v180, v164
	v_cvt_pk_bf16_f32 v87, v210, v209
	v_cvt_pk_bf16_f32 v88, v211, v212
	v_cvt_pk_bf16_f32 v89, v213, v214
	s_waitcnt lgkmcnt(3)
	s_nop 0
	v_mfma_f32_32x32x16_bf16 v[34:49], v[90:93], v[86:89], v[34:49]
	s_waitcnt lgkmcnt(2)
	v_mfma_f32_32x32x16_bf16 v[50:65], v[234:237], v[86:89], v[50:65]
	v_cvt_pk_bf16_f32 v86, v215, v216
	v_cvt_pk_bf16_f32 v87, v163, v165
	v_cvt_pk_bf16_f32 v88, v181, v182
	v_cvt_pk_bf16_f32 v89, v183, v185
	s_waitcnt lgkmcnt(1)
	s_nop 0
	v_mfma_f32_32x32x16_bf16 v[2:17], v[238:241], v[86:89], v[34:49]
	s_waitcnt lgkmcnt(0)
	v_mfma_f32_32x32x16_bf16 v[18:33], v[94:97], v[86:89], v[50:65]

; DI unsigned pack2(float a, float b) { f32x2 v = {a, b}; bf16x2_t r = __builtin_convertvector(v, bf16x2_t); return __builtin_bit_cast(unsigned, r); }
; DI f32x16 mfma32(bf16x8 a, bf16x8 b, f32x16 c) { return __builtin_amdgcn_mfma_f32_32x32x16_bf16(a, b, c, 0, 0, 0); }
;     ...
;   const float mn = fmaxf(m, mx); const float alpha = __builtin_amdgcn_exp2f(m - mn);
;   const float neg = (MODE == 2 && !lanesel) ? NINF : -mn;
;   float ps = 0.f;
; #pragma unroll
;   for (int k2 = 0; k2 < 2; ++k2)
; #pragma unroll
;     for (int i = 0; i < 16; ++i) {
;       if (!(HM & (1 << k2))) continue;
;       const float pv = (MODE == 1) ? __builtin_amdgcn_exp2f(s[k2][i] + neg) : __builtin_amdgcn_exp2f(fmaf(s[k2][i], L2E, neg));
;       s[k2][i] = pv; ps += pv;
;     }
;   l = l * alpha + ps;
;   if (__builtin_amdgcn_ballot_w64(mn != m) != 0ull) {
; #pragma unroll
;     for (int dt = 0; dt < 2; ++dt)
; #pragma unroll
;       for (int i = 0; i < 16; ++i) o[dt][i] *= alpha;
;   }
;   m = mn;
; #pragma unroll
;   for (int st = 0; st < 4; ++st) {
;     if (!(HM & (1 << (st >> 1)))) continue;
;     const int k2 = st >> 1, b8 = 8 * (st & 1);
;     const u32x4 pw = {pack2(s[k2][b8], s[k2][b8 + 1]), pack2(s[k2][b8 + 2], s[k2][b8 + 3]), pack2(s[k2][b8 + 4], s[k2][b8 + 5]), pack2(s[k2][b8 + 6], s[k2][b8 + 7])};
;     const bf16x8 pb = __builtin_bit_cast(bf16x8, pw);
; #pragma unroll
;     for (int dt = 0; dt < 2; ++dt) {
;       const s16x4 lo = *(const s16x4*)(Vs + (32 * dt + r) * LSTR + 16 * st + 4 * h);
;       const s16x4 hi = *(const s16x4*)(Vs + (32 * dt + r) * LSTR + 16 * st + 8 + 4 * h);
;       const bf16x8 a = __builtin_shufflevector(lo, hi, 0, 1, 2, 3, 4, 5, 6, 7);
;       o[dt] = mfma32(a, pb, o[dt]);
;     }
;   }
.LBB0_938:
	v_fma_f32 v82, v82, s34, -v160
	v_exp_f32_e32 v82, v82
	v_fma_f32 v83, v83, s34, -v160
	v_exp_f32_e32 v83, v83
	v_fma_f32 v84, v84, s34, -v160
	v_exp_f32_e32 v84, v84
	v_fma_f32 v85, v85, s34, -v160
	v_exp_f32_e32 v85, v85
	v_fma_f32 v86, v86, s34, -v160
	v_add_f32_e32 v162, 0, v82
	v_exp_f32_e32 v86, v86
	v_fma_f32 v87, v87, s34, -v160
	v_add_f32_e32 v162, v83, v162
	v_exp_f32_e32 v87, v87
	v_fma_f32 v88, v88, s34, -v160
	v_add_f32_e32 v162, v84, v162
	v_exp_f32_e32 v88, v88
	v_fma_f32 v89, v89, s34, -v160
	v_add_f32_e32 v162, v85, v162
	v_exp_f32_e32 v89, v89
	v_fma_f32 v90, v90, s34, -v160
	v_add_f32_e32 v162, v86, v162
	v_exp_f32_e32 v90, v90
	v_fma_f32 v91, v91, s34, -v160
	v_add_f32_e32 v162, v87, v162
	v_exp_f32_e32 v91, v91
	v_fma_f32 v92, v92, s34, -v160
	v_add_f32_e32 v162, v88, v162
	v_exp_f32_e32 v92, v92
	v_fma_f32 v93, v93, s34, -v160
	v_add_f32_e32 v162, v89, v162
	v_exp_f32_e32 v93, v93
	v_fma_f32 v94, v94, s34, -v160
	v_add_f32_e32 v162, v90, v162
	v_exp_f32_e32 v94, v94
	v_fma_f32 v95, v95, s34, -v160
	v_add_f32_e32 v162, v91, v162
	v_exp_f32_e32 v95, v95
	v_fma_f32 v96, v96, s34, -v160
	v_add_f32_e32 v162, v92, v162
	v_exp_f32_e32 v96, v96
	v_fma_f32 v97, v97, s34, -v160
	v_add_f32_e32 v162, v93, v162
	v_exp_f32_e32 v97, v97
	v_fma_f32 v66, v66, s34, -v160
	v_add_f32_e32 v162, v94, v162
	v_exp_f32_e32 v163, v66
	v_fma_f32 v67, v67, s34, -v160
	v_add_f32_e32 v162, v95, v162
	v_exp_f32_e32 v164, v67
	v_fma_f32 v67, v68, s34, -v160
	v_add_f32_e32 v162, v96, v162
	v_exp_f32_e32 v165, v67
	v_fma_f32 v67, v69, s34, -v160
	v_add_f32_e32 v162, v97, v162
	v_exp_f32_e32 v180, v67
	v_fma_f32 v67, v70, s34, -v160
	v_add_f32_e32 v66, v163, v162
	v_exp_f32_e32 v181, v67
	v_fma_f32 v67, v71, s34, -v160
	v_add_f32_e32 v66, v164, v66
	v_exp_f32_e32 v182, v67
	v_fma_f32 v67, v72, s34, -v160
	v_add_f32_e32 v66, v165, v66
	v_exp_f32_e32 v183, v67
	v_fma_f32 v67, v73, s34, -v160
	v_add_f32_e32 v66, v180, v66
	v_exp_f32_e32 v184, v67
	v_fma_f32 v67, v74, s34, -v160
	v_add_f32_e32 v66, v181, v66
	v_exp_f32_e32 v185, v67
	v_fma_f32 v67, v75, s34, -v160
	v_add_f32_e32 v66, v182, v66
	v_exp_f32_e32 v186, v67
	v_fma_f32 v67, v76, s34, -v160
	v_add_f32_e32 v66, v183, v66
	v_exp_f32_e32 v187, v67
	v_fma_f32 v67, v77, s34, -v160
	v_add_f32_e32 v66, v184, v66
	v_exp_f32_e32 v188, v67
	v_fma_f32 v67, v78, s34, -v160
	v_add_f32_e32 v66, v185, v66
	v_exp_f32_e32 v78, v67
	v_fma_f32 v67, v79, s34, -v160
	v_add_f32_e32 v66, v186, v66
	v_exp_f32_e32 v79, v67
	v_fma_f32 v67, v80, s34, -v160
	v_add_f32_e32 v66, v187, v66
	v_exp_f32_e32 v80, v67
	v_fma_f32 v67, v81, s34, -v160
	v_add_f32_e32 v66, v188, v66
	v_exp_f32_e32 v81, v67
	v_add_f32_e32 v66, v78, v66
	v_add_f32_e32 v66, v79, v66
	v_add_f32_e32 v66, v80, v66
	v_add_f32_e32 v162, v81, v66
	v_fmac_f32_e32 v162, v161, v0
	v_add_u32_e32 v0, 0x2000, v198
	v_add_u32_e32 v242, 0x3000, v198
	ds_read2_b64 v[70:73], v0 offset0:128 offset1:130
	ds_read2_b64 v[74:77], v0 offset0:132 offset1:134
	ds_read2_b64 v[234:237], v242 offset0:192 offset1:194
	ds_read2_b64 v[238:241], v242 offset0:196 offset1:198
	v_cvt_pk_bf16_f32 v66, v82, v83
	v_cvt_pk_bf16_f32 v67, v84, v85
	v_cvt_pk_bf16_f32 v68, v86, v87
	v_cvt_pk_bf16_f32 v69, v88, v89
	v_add_u32_e32 v82, 0x3000, v198
	s_waitcnt lgkmcnt(3)
	v_mfma_f32_32x32x16_bf16 v[34:49], v[70:73], v[66:69], v[2:17]
	ds_read2_b64 v[70:73], v0 offset0:136 offset1:138
	s_waitcnt lgkmcnt(2)
	v_mfma_f32_32x32x16_bf16 v[50:65], v[234:237], v[66:69], v[18:33]
	ds_read2_b64 v[234:237], v242 offset0:200 offset1:202
	v_cvt_pk_bf16_f32 v66, v90, v91
	v_cvt_pk_bf16_f32 v67, v92, v93
	v_cvt_pk_bf16_f32 v68, v94, v95
	v_cvt_pk_bf16_f32 v69, v96, v97
	s_waitcnt lgkmcnt(2)
	s_nop 0
	v_mfma_f32_32x32x16_bf16 v[50:65], v[238:241], v[66:69], v[50:65]
	ds_read2_b64 v[238:241], v0 offset0:140 offset1:142
	v_mfma_f32_32x32x16_bf16 v[34:49], v[74:77], v[66:69], v[34:49]
	ds_read2_b64 v[74:77], v242 offset0:204 offset1:206
	v_cvt_pk_bf16_f32 v66, v163, v164
	v_cvt_pk_bf16_f32 v67, v165, v180
	v_cvt_pk_bf16_f32 v68, v181, v182
	v_cvt_pk_bf16_f32 v69, v183, v184
	s_waitcnt lgkmcnt(3)
	s_nop 0
	v_mfma_f32_32x32x16_bf16 v[34:49], v[70:73], v[66:69], v[34:49]
	s_waitcnt lgkmcnt(2)
	v_mfma_f32_32x32x16_bf16 v[50:65], v[234:237], v[66:69], v[50:65]
	v_cvt_pk_bf16_f32 v66, v185, v186
	v_cvt_pk_bf16_f32 v67, v187, v188
	v_cvt_pk_bf16_f32 v68, v78, v79
	v_cvt_pk_bf16_f32 v69, v80, v81
	s_waitcnt lgkmcnt(1)
	s_nop 0
	v_mfma_f32_32x32x16_bf16 v[2:17], v[238:241], v[66:69], v[34:49]
	s_waitcnt lgkmcnt(0)
	v_mfma_f32_32x32x16_bf16 v[18:33], v[74:77], v[66:69], v[50:65]

; DI unsigned pack2(float a, float b) { f32x2 v = {a, b}; bf16x2_t r = __builtin_convertvector(v, bf16x2_t); return __builtin_bit_cast(unsigned, r); }
; DI f32x16 mfma32(bf16x8 a, bf16x8 b, f32x16 c) { return __builtin_amdgcn_mfma_f32_32x32x16_bf16(a, b, c, 0, 0, 0); }
;     ...
;   const float mn = fmaxf(m, mx); const float alpha = __builtin_amdgcn_exp2f(m - mn);
;   const float neg = (MODE == 2 && !lanesel) ? NINF : -mn;
;   float ps = 0.f;
; #pragma unroll
;   for (int k2 = 0; k2 < 2; ++k2)
; #pragma unroll
;     for (int i = 0; i < 16; ++i) {
;       if (!(HM & (1 << k2))) continue;
;       const float pv = (MODE == 1) ? __builtin_amdgcn_exp2f(s[k2][i] + neg) : __builtin_amdgcn_exp2f(fmaf(s[k2][i], L2E, neg));
;       s[k2][i] = pv; ps += pv;
;     }
;   l = l * alpha + ps;
;   if (__builtin_amdgcn_ballot_w64(mn != m) != 0ull) {
; #pragma unroll
;     for (int dt = 0; dt < 2; ++dt)
; #pragma unroll
;       for (int i = 0; i < 16; ++i) o[dt][i] *= alpha;
;   }
;   m = mn;
; #pragma unroll
;   for (int st = 0; st < 4; ++st) {
;     if (!(HM & (1 << (st >> 1)))) continue;
;     const int k2 = st >> 1, b8 = 8 * (st & 1);
;     const u32x4 pw = {pack2(s[k2][b8], s[k2][b8 + 1]), pack2(s[k2][b8 + 2], s[k2][b8 + 3]), pack2(s[k2][b8 + 4], s[k2][b8 + 5]), pack2(s[k2][b8 + 6], s[k2][b8 + 7])};
;     const bf16x8 pb = __builtin_bit_cast(bf16x8, pw);
; #pragma unroll
;     for (int dt = 0; dt < 2; ++dt) {
;       const s16x4 lo = *(const s16x4*)(Vs + (32 * dt + r) * LSTR + 16 * st + 4 * h);
;       const s16x4 hi = *(const s16x4*)(Vs + (32 * dt + r) * LSTR + 16 * st + 8 + 4 * h);
;       const bf16x8 a = __builtin_shufflevector(lo, hi, 0, 1, 2, 3, 4, 5, 6, 7);
;       o[dt] = mfma32(a, pb, o[dt]);
;     }
;   }
.LBB0_962:
	v_fma_f32 v86, v86, s34, -v159
	v_exp_f32_e32 v86, v86
	v_fma_f32 v87, v87, s34, -v159
	v_exp_f32_e32 v87, v87
	v_fma_f32 v88, v88, s34, -v159
	v_exp_f32_e32 v88, v88
	v_fma_f32 v89, v89, s34, -v159
	v_exp_f32_e32 v89, v89
	v_fma_f32 v90, v90, s34, -v159
	v_add_f32_e32 v209, 0, v86
	v_exp_f32_e32 v90, v90
	v_fma_f32 v194, v194, s34, -v159
	v_add_f32_e32 v209, v87, v209
	v_exp_f32_e32 v194, v194
	v_fma_f32 v193, v193, s34, -v159
	v_add_f32_e32 v209, v88, v209
	v_exp_f32_e32 v193, v193
	v_fma_f32 v195, v195, s34, -v159
	v_add_f32_e32 v209, v89, v209
	v_exp_f32_e32 v195, v195
	v_fma_f32 v190, v190, s34, -v159
	v_add_f32_e32 v209, v90, v209
	v_exp_f32_e32 v190, v190
	v_fma_f32 v192, v192, s34, -v159
	v_add_f32_e32 v209, v194, v209
	v_exp_f32_e32 v192, v192
	v_fma_f32 v191, v191, s34, -v159
	v_add_f32_e32 v209, v193, v209
	v_exp_f32_e32 v191, v191
	v_fma_f32 v189, v189, s34, -v159
	v_add_f32_e32 v209, v195, v209
	v_exp_f32_e32 v189, v189
	v_fma_f32 v188, v188, s34, -v159
	v_add_f32_e32 v209, v190, v209
	v_exp_f32_e32 v188, v188
	v_fma_f32 v187, v187, s34, -v159
	v_add_f32_e32 v209, v192, v209
	v_exp_f32_e32 v187, v187
	v_fma_f32 v186, v186, s34, -v159
	v_add_f32_e32 v209, v191, v209
	v_exp_f32_e32 v186, v186
	v_fma_f32 v184, v184, s34, -v159
	v_add_f32_e32 v209, v189, v209
	v_exp_f32_e32 v184, v184
	v_fma_f32 v180, v180, s34, -v159
	v_add_f32_e32 v209, v188, v209
	v_exp_f32_e32 v180, v180
	v_fma_f32 v164, v164, s34, -v159
	v_add_f32_e32 v209, v187, v209
	v_exp_f32_e32 v164, v164
	v_fma_f32 v161, v161, s34, -v159
	v_add_f32_e32 v209, v186, v209
	v_exp_f32_e32 v210, v161
	v_add_f32_e32 v209, v184, v209
	v_add_f32_e32 v209, v180, v209
	v_add_f32_e32 v209, v164, v209
	v_fma_f32 v97, v97, s34, -v159
	v_add_f32_e32 v161, v210, v209
	v_exp_f32_e32 v209, v97
	v_fma_f32 v92, v92, s34, -v159
	v_exp_f32_e32 v211, v92
	v_fma_f32 v91, v91, s34, -v159
	v_exp_f32_e32 v212, v91
	v_add_f32_e32 v97, v209, v161
	v_add_f32_e32 v92, v211, v97
	v_cvt_pk_bf16_f32 v86, v86, v87
	v_add_f32_e32 v91, v212, v92
	v_fma_f32 v92, v93, s34, -v159
	v_exp_f32_e32 v213, v92
	v_fma_f32 v92, v94, s34, -v159
	v_exp_f32_e32 v214, v92
	v_fma_f32 v92, v95, s34, -v159
	v_exp_f32_e32 v215, v92
	v_fma_f32 v92, v96, s34, -v159
	v_exp_f32_e32 v216, v92
	v_fma_f32 v92, v163, s34, -v159
	v_add_f32_e32 v91, v213, v91
	v_exp_f32_e32 v163, v92
	v_fma_f32 v92, v165, s34, -v159
	v_add_f32_e32 v91, v214, v91
	v_exp_f32_e32 v165, v92
	v_fma_f32 v92, v181, s34, -v159
	v_add_f32_e32 v91, v215, v91
	v_exp_f32_e32 v181, v92
	v_fma_f32 v92, v182, s34, -v159
	v_add_f32_e32 v91, v216, v91
	v_exp_f32_e32 v182, v92
	v_fma_f32 v92, v183, s34, -v159
	v_add_f32_e32 v91, v163, v91
	v_exp_f32_e32 v183, v92
	v_fma_f32 v92, v185, s34, -v159
	v_add_f32_e32 v91, v165, v91
	v_exp_f32_e32 v185, v92
	v_add_f32_e32 v91, v181, v91
	v_add_f32_e32 v91, v182, v91
	v_add_f32_e32 v91, v183, v91
	v_add_f32_e32 v161, v185, v91
	v_fmac_f32_e32 v161, v162, v0
	v_add_u32_e32 v0, 0x6800, v198
	v_cvt_pk_bf16_f32 v87, v88, v89
	v_cvt_pk_bf16_f32 v88, v90, v194
	v_add_u32_e32 v242, 0x7800, v198
	ds_read2_b64 v[90:93], v0 offset0:128 offset1:130
	ds_read2_b64 v[94:97], v0 offset0:132 offset1:134
	ds_read2_b64 v[234:237], v242 offset0:192 offset1:194
	ds_read2_b64 v[238:241], v242 offset0:196 offset1:198
	v_cvt_pk_bf16_f32 v89, v193, v195
	v_add_u32_e32 v193, 0x7800, v198
	s_mov_b64 s[6:7], 0
	s_waitcnt lgkmcnt(3)
	v_mfma_f32_32x32x16_bf16 v[34:49], v[90:93], v[86:89], v[2:17]
	ds_read2_b64 v[90:93], v0 offset0:136 offset1:138
	s_waitcnt lgkmcnt(2)
	v_mfma_f32_32x32x16_bf16 v[50:65], v[234:237], v[86:89], v[18:33]
	ds_read2_b64 v[234:237], v242 offset0:200 offset1:202
	v_cvt_pk_bf16_f32 v86, v190, v192
	v_cvt_pk_bf16_f32 v87, v191, v189
	v_cvt_pk_bf16_f32 v88, v188, v187
	v_cvt_pk_bf16_f32 v89, v186, v184
	s_waitcnt lgkmcnt(2)
	s_nop 0
	v_mfma_f32_32x32x16_bf16 v[50:65], v[238:241], v[86:89], v[50:65]
	ds_read2_b64 v[238:241], v0 offset0:140 offset1:142
	v_mfma_f32_32x32x16_bf16 v[34:49], v[94:97], v[86:89], v[34:49]
	ds_read2_b64 v[94:97], v242 offset0:204 offset1:206
	v_cvt_pk_bf16_f32 v86, v180, v164
	v_cvt_pk_bf16_f32 v87, v210, v209
	v_cvt_pk_bf16_f32 v88, v211, v212
	v_cvt_pk_bf16_f32 v89, v213, v214
	s_waitcnt lgkmcnt(3)
	s_nop 0
	v_mfma_f32_32x32x16_bf16 v[34:49], v[90:93], v[86:89], v[34:49]
	s_waitcnt lgkmcnt(2)
	v_mfma_f32_32x32x16_bf16 v[50:65], v[234:237], v[86:89], v[50:65]
	v_cvt_pk_bf16_f32 v86, v215, v216
	v_cvt_pk_bf16_f32 v87, v163, v165
	v_cvt_pk_bf16_f32 v88, v181, v182
	v_cvt_pk_bf16_f32 v89, v183, v185
	s_waitcnt lgkmcnt(1)
	s_nop 0
	v_mfma_f32_32x32x16_bf16 v[2:17], v[238:241], v[86:89], v[34:49]
	s_waitcnt lgkmcnt(0)
	v_mfma_f32_32x32x16_bf16 v[18:33], v[94:97], v[86:89], v[50:65]

; DI unsigned pack2(float a, float b) { f32x2 v = {a, b}; bf16x2_t r = __builtin_convertvector(v, bf16x2_t); return __builtin_bit_cast(unsigned, r); }
; DI f32x16 mfma32(bf16x8 a, bf16x8 b, f32x16 c) { return __builtin_amdgcn_mfma_f32_32x32x16_bf16(a, b, c, 0, 0, 0); }
;     ...
;   const float mn = fmaxf(m, mx); const float alpha = __builtin_amdgcn_exp2f(m - mn);
;   const float neg = (MODE == 2 && !lanesel) ? NINF : -mn;
;   float ps = 0.f;
; #pragma unroll
;   for (int k2 = 0; k2 < 2; ++k2)
; #pragma unroll
;     for (int i = 0; i < 16; ++i) {
;       if (!(HM & (1 << k2))) continue;
;       const float pv = (MODE == 1) ? __builtin_amdgcn_exp2f(s[k2][i] + neg) : __builtin_amdgcn_exp2f(fmaf(s[k2][i], L2E, neg));
;       s[k2][i] = pv; ps += pv;
;     }
;   l = l * alpha + ps;
;   if (__builtin_amdgcn_ballot_w64(mn != m) != 0ull) {
; #pragma unroll
;     for (int dt = 0; dt < 2; ++dt)
; #pragma unroll
;       for (int i = 0; i < 16; ++i) o[dt][i] *= alpha;
;   }
;   m = mn;
; #pragma unroll
;   for (int st = 0; st < 4; ++st) {
;     if (!(HM & (1 << (st >> 1)))) continue;
;     const int k2 = st >> 1, b8 = 8 * (st & 1);
;     const u32x4 pw = {pack2(s[k2][b8], s[k2][b8 + 1]), pack2(s[k2][b8 + 2], s[k2][b8 + 3]), pack2(s[k2][b8 + 4], s[k2][b8 + 5]), pack2(s[k2][b8 + 6], s[k2][b8 + 7])};
;     const bf16x8 pb = __builtin_bit_cast(bf16x8, pw);
; #pragma unroll
;     for (int dt = 0; dt < 2; ++dt) {
;       const s16x4 lo = *(const s16x4*)(Vs + (32 * dt + r) * LSTR + 16 * st + 4 * h);
;       const s16x4 hi = *(const s16x4*)(Vs + (32 * dt + r) * LSTR + 16 * st + 8 + 4 * h);
;       const bf16x8 a = __builtin_shufflevector(lo, hi, 0, 1, 2, 3, 4, 5, 6, 7);
;       o[dt] = mfma32(a, pb, o[dt]);
;     }
;   }
.LBB0_966:
	v_fma_f32 v82, v82, s34, -v159
	v_exp_f32_e32 v82, v82
	v_fma_f32 v83, v83, s34, -v159
	v_exp_f32_e32 v83, v83
	v_fma_f32 v84, v84, s34, -v159
	v_exp_f32_e32 v84, v84
	v_fma_f32 v85, v85, s34, -v159
	v_exp_f32_e32 v85, v85
	v_fma_f32 v86, v86, s34, -v159
	v_add_f32_e32 v161, 0, v82
	v_exp_f32_e32 v86, v86
	v_fma_f32 v87, v87, s34, -v159
	v_add_f32_e32 v161, v83, v161
	v_exp_f32_e32 v87, v87
	v_fma_f32 v88, v88, s34, -v159
	v_add_f32_e32 v161, v84, v161
	v_exp_f32_e32 v88, v88
	v_fma_f32 v89, v89, s34, -v159
	v_add_f32_e32 v161, v85, v161
	v_exp_f32_e32 v89, v89
	v_fma_f32 v90, v90, s34, -v159
	v_add_f32_e32 v161, v86, v161
	v_exp_f32_e32 v90, v90
	v_fma_f32 v91, v91, s34, -v159
	v_add_f32_e32 v161, v87, v161
	v_exp_f32_e32 v91, v91
	v_fma_f32 v92, v92, s34, -v159
	v_add_f32_e32 v161, v88, v161
	v_exp_f32_e32 v92, v92
	v_fma_f32 v93, v93, s34, -v159
	v_add_f32_e32 v161, v89, v161
	v_exp_f32_e32 v93, v93
	v_fma_f32 v94, v94, s34, -v159
	v_add_f32_e32 v161, v90, v161
	v_exp_f32_e32 v94, v94
	v_fma_f32 v95, v95, s34, -v159
	v_add_f32_e32 v161, v91, v161
	v_exp_f32_e32 v95, v95
	v_fma_f32 v96, v96, s34, -v159
	v_add_f32_e32 v161, v92, v161
	v_exp_f32_e32 v96, v96
	v_fma_f32 v97, v97, s34, -v159
	v_add_f32_e32 v161, v93, v161
	v_exp_f32_e32 v97, v97
	v_fma_f32 v66, v66, s34, -v159
	v_add_f32_e32 v161, v94, v161
	v_exp_f32_e32 v163, v66
	v_fma_f32 v67, v67, s34, -v159
	v_add_f32_e32 v161, v95, v161
	v_exp_f32_e32 v164, v67
	v_fma_f32 v67, v68, s34, -v159
	v_add_f32_e32 v161, v96, v161
	v_exp_f32_e32 v165, v67
	v_fma_f32 v67, v69, s34, -v159
	v_add_f32_e32 v161, v97, v161
	v_exp_f32_e32 v180, v67
	v_fma_f32 v67, v70, s34, -v159
	v_add_f32_e32 v66, v163, v161
	v_exp_f32_e32 v181, v67
	v_fma_f32 v67, v71, s34, -v159
	v_add_f32_e32 v66, v164, v66
	v_exp_f32_e32 v182, v67
	v_fma_f32 v67, v72, s34, -v159
	v_add_f32_e32 v66, v165, v66
	v_exp_f32_e32 v183, v67
	v_fma_f32 v67, v73, s34, -v159
	v_add_f32_e32 v66, v180, v66
	v_exp_f32_e32 v184, v67
	v_fma_f32 v67, v74, s34, -v159
	v_add_f32_e32 v66, v181, v66
	v_exp_f32_e32 v185, v67
	v_fma_f32 v67, v75, s34, -v159
	v_add_f32_e32 v66, v182, v66
	v_exp_f32_e32 v186, v67
	v_fma_f32 v67, v76, s34, -v159
	v_add_f32_e32 v66, v183, v66
	v_exp_f32_e32 v187, v67
	v_fma_f32 v67, v77, s34, -v159
	v_add_f32_e32 v66, v184, v66
	v_exp_f32_e32 v188, v67
	v_fma_f32 v67, v78, s34, -v159
	v_add_f32_e32 v66, v185, v66
	v_exp_f32_e32 v78, v67
	v_fma_f32 v67, v79, s34, -v159
	v_add_f32_e32 v66, v186, v66
	v_exp_f32_e32 v79, v67
	v_fma_f32 v67, v80, s34, -v159
	v_add_f32_e32 v66, v187, v66
	v_exp_f32_e32 v80, v67
	v_fma_f32 v67, v81, s34, -v159
	v_add_f32_e32 v66, v188, v66
	v_exp_f32_e32 v81, v67
	v_add_f32_e32 v66, v78, v66
	v_add_f32_e32 v66, v79, v66
	v_add_f32_e32 v66, v80, v66
	v_add_f32_e32 v161, v81, v66
	v_fmac_f32_e32 v161, v162, v0
	v_add_u32_e32 v0, 0x6800, v198
	v_add_u32_e32 v242, 0x7800, v198
	ds_read2_b64 v[70:73], v0 offset0:128 offset1:130
	ds_read2_b64 v[74:77], v0 offset0:132 offset1:134
	ds_read2_b64 v[234:237], v242 offset0:192 offset1:194
	ds_read2_b64 v[238:241], v242 offset0:196 offset1:198
	v_cvt_pk_bf16_f32 v66, v82, v83
	v_cvt_pk_bf16_f32 v67, v84, v85
	v_cvt_pk_bf16_f32 v68, v86, v87
	v_cvt_pk_bf16_f32 v69, v88, v89
	v_add_u32_e32 v82, 0x7800, v198
	s_waitcnt lgkmcnt(3)
	v_mfma_f32_32x32x16_bf16 v[34:49], v[70:73], v[66:69], v[2:17]
	ds_read2_b64 v[70:73], v0 offset0:136 offset1:138
	s_waitcnt lgkmcnt(2)
	v_mfma_f32_32x32x16_bf16 v[50:65], v[234:237], v[66:69], v[18:33]
	ds_read2_b64 v[234:237], v242 offset0:200 offset1:202
	v_cvt_pk_bf16_f32 v66, v90, v91
	v_cvt_pk_bf16_f32 v67, v92, v93
	v_cvt_pk_bf16_f32 v68, v94, v95
	v_cvt_pk_bf16_f32 v69, v96, v97
	s_waitcnt lgkmcnt(2)
	s_nop 0
	v_mfma_f32_32x32x16_bf16 v[50:65], v[238:241], v[66:69], v[50:65]
	ds_read2_b64 v[238:241], v0 offset0:140 offset1:142
	v_mfma_f32_32x32x16_bf16 v[34:49], v[74:77], v[66:69], v[34:49]
	ds_read2_b64 v[74:77], v242 offset0:204 offset1:206
	v_cvt_pk_bf16_f32 v66, v163, v164
	v_cvt_pk_bf16_f32 v67, v165, v180
	v_cvt_pk_bf16_f32 v68, v181, v182
	v_cvt_pk_bf16_f32 v69, v183, v184
	s_waitcnt lgkmcnt(3)
	s_nop 0
	v_mfma_f32_32x32x16_bf16 v[34:49], v[70:73], v[66:69], v[34:49]
	s_waitcnt lgkmcnt(2)
	v_mfma_f32_32x32x16_bf16 v[50:65], v[234:237], v[66:69], v[50:65]
	v_cvt_pk_bf16_f32 v66, v185, v186
	v_cvt_pk_bf16_f32 v67, v187, v188
	v_cvt_pk_bf16_f32 v68, v78, v79
	v_cvt_pk_bf16_f32 v69, v80, v81
	s_waitcnt lgkmcnt(1)
	s_nop 0
	v_mfma_f32_32x32x16_bf16 v[2:17], v[238:241], v[66:69], v[34:49]
	s_waitcnt lgkmcnt(0)
	v_mfma_f32_32x32x16_bf16 v[18:33], v[74:77], v[66:69], v[50:65]
